# W_in^T stored with 128-B chunk XOR swizzle by row (c ^ (n&31)); P1 main K-loop reads B through the same map (spreads the 4-KiB-stride rows over cache sets/channels)
# speedup vs baseline: 1.0103x; 1.0103x over previous
.LBB0_19:
	s_load_dwordx16 s[76:91], s[0:1], 0x80
	s_load_dwordx4 s[28:31], s[0:1], 0x110
	s_waitcnt lgkmcnt(0)
	s_cmp_gt_i32 s28, 0
	s_cselect_b64 s[4:5], -1, 0
	s_cmp_lt_i32 s29, 1
	s_cselect_b64 s[6:7], -1, 0
	s_or_b64 s[4:5], s[4:5], s[6:7]
	s_and_b64 vcc, exec, s[4:5]
	s_cbranch_vccnz .LBB0_123
	s_cmpk_gt_i32 s2, 0x35e1
	s_cbranch_scc1 .LBB0_78
	s_load_dwordx2 s[30:31], s[0:1], 0x40
	s_load_dwordx2 s[32:33], s[0:1], 0xb0
	s_load_dwordx2 s[34:35], s[0:1], 0xc8
	s_load_dwordx2 s[36:37], s[0:1], 0xd0
	s_load_dwordx2 s[38:39], s[0:1], 0xe0
	s_load_dword s3, s[0:1], 0x120
	v_lshrrev_b32_e32 v0, 4, v204
	v_and_b32_e32 v1, 15, v204
	v_lshlrev_b32_e32 v1, 4, v1
	v_lshrrev_b32_e32 v2, 3, v204
	v_and_b32_e32 v3, 7, v204
	v_add_u32_e32 v8, 0, v0
	v_mul_u32_u24_e32 v8, 0x104, v8
	v_add3_u32 v8, v8, v1, 32
	v_add_u32_e32 v72, 0x4100, v8
	v_add_u32_e32 v9, 16, v0
	v_mul_u32_u24_e32 v9, 0x104, v9
	v_add3_u32 v9, v9, v1, 32
	v_add_u32_e32 v73, 0x4100, v9
	v_add_u32_e32 v10, 32, v0
	v_mul_u32_u24_e32 v10, 0x104, v10
	v_add3_u32 v10, v10, v1, 32
	v_add_u32_e32 v74, 0x4100, v10
	v_add_u32_e32 v11, 48, v0
	v_mul_u32_u24_e32 v11, 0x104, v11
	v_add3_u32 v11, v11, v1, 32
	v_add_u32_e32 v75, 0x4100, v11
	v_mul_u32_u24_e32 v12, 0x820, v3
	v_lshl_add_u32 v12, v2, 2, v12
	v_add_u32_e32 v12, 32, v12
	v_add_u32_e32 v13, 0x410, v12
	v_add_u32_e32 v76, 0x4100, v12
	v_add_u32_e32 v77, 0x4100, v13
	v_lshlrev_b32_e32 v14, 12, v2
	v_lshl_add_u32 v14, v3, 4, v14
	v_add_u32_e32 v78, 0, v0
	v_add_u32_e32 v79, 16, v0
	v_add_u32_e32 v80, 32, v0
	v_add_u32_e32 v81, 48, v0
	s_waitcnt lgkmcnt(0)
	s_mov_b32 s4, s2

.Ltr_p_d0:
	s_mul_i32 s6, s5, 6242
	s_lshr_b32 s6, s6, 20
	s_mul_i32 s7, s6, 168
	s_sub_u32 s7, s5, s7
	s_mov_b32 s12, 0xa800
	s_movk_i32 s13, 31
	s_mul_i32 s8, s6, 0x2a0000
	s_lshl_b32 s9, s7, 8
	s_add_u32 s8, s8, s9
	s_add_u32 s10, s30, s8
	s_addc_u32 s11, s31, 0
	s_lshl_b32 s8, s7, 18
	s_add_u32 s8, s8, 0x13288000
	s_add_u32 s14, s94, s8
	s_addc_u32 s15, s95, 0
	s_branch .Ltr_p_end
.Ltr_p_d1:
	s_lshr_b32 s6, s5, 4
	s_and_b32 s7, s5, 15
	s_mov_b32 s12, 0x1000
	s_movk_i32 s13, 0
	s_mul_i32 s8, s6, 0x40000
	s_lshl_b32 s9, s7, 8
	s_add_u32 s8, s8, s9
	s_add_u32 s10, s32, s8
	s_addc_u32 s11, s33, 0
	s_lshl_b32 s8, s7, 18
	s_add_u32 s8, s8, 0x17e88000
	s_add_u32 s14, s94, s8
	s_addc_u32 s15, s95, 0
	s_branch .Ltr_p_end
.Ltr_p_d2:
	s_lshr_b32 s6, s5, 5
	s_and_b32 s7, s5, 31
	s_mov_b32 s12, 0x2000
	s_movk_i32 s13, 0
	s_mul_i32 s8, s6, 0x80000
	s_lshl_b32 s9, s7, 8
	s_add_u32 s8, s8, s9
	s_add_u32 s10, s34, s8
	s_addc_u32 s11, s35, 0
	s_lshl_b32 s8, s7, 18
	s_add_u32 s8, s8, 0x18288000
	s_add_u32 s14, s94, s8
	s_addc_u32 s15, s95, 0
	s_branch .Ltr_p_end
.Ltr_p_d3:
	s_lshr_b32 s6, s5, 5
	s_and_b32 s7, s5, 31
	s_mov_b32 s12, 0x2000
	s_movk_i32 s13, 0
	s_mul_i32 s8, s6, 0x80000
	s_lshl_b32 s9, s7, 8
	s_add_u32 s8, s8, s9
	s_add_u32 s10, s36, s8
	s_addc_u32 s11, s37, 0
	s_lshl_b32 s8, s7, 18
	s_add_u32 s8, s8, 0x18a88000
	s_add_u32 s14, s94, s8
	s_addc_u32 s15, s95, 0
	s_branch .Ltr_p_end
.Ltr_p_d4:
	s_lshr_b32 s6, s5, 5
	s_and_b32 s7, s5, 31
	s_mov_b32 s12, 0x2000
	s_movk_i32 s13, 0
	s_mul_i32 s8, s6, 0x80000
	s_lshl_b32 s9, s7, 8
	s_add_u32 s8, s8, s9
	s_add_u32 s10, s38, s8
	s_addc_u32 s11, s39, 0
	s_lshl_b32 s8, s7, 18
	s_add_u32 s8, s8, 0x19288000
	s_add_u32 s14, s94, s8
	s_addc_u32 s15, s95, 0
.Ltr_p_end:
	s_mov_b64 s[16:17], s[14:15]
	s_mov_b32 s26, s6
	s_mov_b32 s27, s13
	v_mad_u32_u24 v4, v78, s12, v1
	v_mad_u32_u24 v5, v79, s12, v1
	v_mad_u32_u24 v6, v80, s12, v1
	v_mad_u32_u24 v7, v81, s12, v1
	global_load_dwordx4 v[16:19], v4, s[10:11]
	global_load_dwordx4 v[20:23], v5, s[10:11]
	global_load_dwordx4 v[24:27], v6, s[10:11]
	global_load_dwordx4 v[28:31], v7, s[10:11]

.Ltr_a_end:
	v_mad_u32_u24 v4, v78, s12, v1
	v_mad_u32_u24 v5, v79, s12, v1
	v_mad_u32_u24 v6, v80, s12, v1
	v_mad_u32_u24 v7, v81, s12, v1
	global_load_dwordx4 v[32:35], v4, s[10:11]
	global_load_dwordx4 v[36:39], v5, s[10:11]
	global_load_dwordx4 v[40:43], v6, s[10:11]
	global_load_dwordx4 v[44:47], v7, s[10:11]
	s_waitcnt vmcnt(4)
	ds_write2_b32 v8, v16, v17 offset1:1
	ds_write2_b32 v8, v18, v19 offset0:2 offset1:3
	ds_write2_b32 v9, v20, v21 offset1:1
	ds_write2_b32 v9, v22, v23 offset0:2 offset1:3
	ds_write2_b32 v10, v24, v25 offset1:1
	ds_write2_b32 v10, v26, v27 offset0:2 offset1:3
	ds_write2_b32 v11, v28, v29 offset1:1
	ds_write2_b32 v11, v30, v31 offset0:2 offset1:3
	v_and_b32_e32 v82, s27, v2
	v_xor_b32_e32 v82, s26, v82
	v_lshl_add_u32 v82, v82, 7, v14
	v_add_u32_e32 v83, 0x20000, v82
	s_waitcnt lgkmcnt(0)
	s_barrier
	ds_read2_b32 v[48:49], v12 offset1:65
	ds_read2_b32 v[50:51], v12 offset0:130 offset1:195
	ds_read2_b32 v[52:53], v13 offset1:65
	ds_read2_b32 v[54:55], v13 offset0:130 offset1:195
	ds_read2_b32 v[56:57], v12 offset0:32 offset1:97
	ds_read2_b32 v[58:59], v12 offset0:162 offset1:227
	ds_read2_b32 v[60:61], v13 offset0:32 offset1:97
	ds_read2_b32 v[62:63], v13 offset0:162 offset1:227
	s_waitcnt lgkmcnt(4)
	v_cvt_pk_bf16_f32 v64, v48, v49
	v_cvt_pk_bf16_f32 v65, v50, v51
	v_cvt_pk_bf16_f32 v66, v52, v53
	v_cvt_pk_bf16_f32 v67, v54, v55
	s_waitcnt lgkmcnt(0)
	v_cvt_pk_bf16_f32 v68, v56, v57
	v_cvt_pk_bf16_f32 v69, v58, v59
	v_cvt_pk_bf16_f32 v70, v60, v61
	v_cvt_pk_bf16_f32 v71, v62, v63
	global_store_dwordx4 v82, v[64:67], s[16:17]
	global_store_dwordx4 v83, v[68:71], s[16:17]
	s_mov_b64 s[16:17], s[14:15]
	s_mov_b32 s26, s6
	s_mov_b32 s27, s13
	s_mov_b32 s4, s18
	s_cmpk_lt_u32 s4, 0x2300
	s_cbranch_scc0 .Ltr_drain
	s_add_u32 s18, s4, s3
	s_cmpk_lt_u32 s18, 0x2300
	s_cselect_b32 s19, s18, s4
	s_mov_b32 s5, s19

.Ltr_b_end:
	v_mad_u32_u24 v4, v78, s12, v1
	v_mad_u32_u24 v5, v79, s12, v1
	v_mad_u32_u24 v6, v80, s12, v1
	v_mad_u32_u24 v7, v81, s12, v1
	global_load_dwordx4 v[16:19], v4, s[10:11]
	global_load_dwordx4 v[20:23], v5, s[10:11]
	global_load_dwordx4 v[24:27], v6, s[10:11]
	global_load_dwordx4 v[28:31], v7, s[10:11]
	s_waitcnt vmcnt(4)
	ds_write2_b32 v72, v32, v33 offset1:1
	ds_write2_b32 v72, v34, v35 offset0:2 offset1:3
	ds_write2_b32 v73, v36, v37 offset1:1
	ds_write2_b32 v73, v38, v39 offset0:2 offset1:3
	ds_write2_b32 v74, v40, v41 offset1:1
	ds_write2_b32 v74, v42, v43 offset0:2 offset1:3
	ds_write2_b32 v75, v44, v45 offset1:1
	ds_write2_b32 v75, v46, v47 offset0:2 offset1:3
	v_and_b32_e32 v82, s27, v2
	v_xor_b32_e32 v82, s26, v82
	v_lshl_add_u32 v82, v82, 7, v14
	v_add_u32_e32 v83, 0x20000, v82
	s_waitcnt lgkmcnt(0)
	s_barrier
	ds_read2_b32 v[48:49], v76 offset1:65
	ds_read2_b32 v[50:51], v76 offset0:130 offset1:195
	ds_read2_b32 v[52:53], v77 offset1:65
	ds_read2_b32 v[54:55], v77 offset0:130 offset1:195
	ds_read2_b32 v[56:57], v76 offset0:32 offset1:97
	ds_read2_b32 v[58:59], v76 offset0:162 offset1:227
	ds_read2_b32 v[60:61], v77 offset0:32 offset1:97
	ds_read2_b32 v[62:63], v77 offset0:162 offset1:227
	s_waitcnt lgkmcnt(4)
	v_cvt_pk_bf16_f32 v64, v48, v49
	v_cvt_pk_bf16_f32 v65, v50, v51
	v_cvt_pk_bf16_f32 v66, v52, v53
	v_cvt_pk_bf16_f32 v67, v54, v55
	s_waitcnt lgkmcnt(0)
	v_cvt_pk_bf16_f32 v68, v56, v57
	v_cvt_pk_bf16_f32 v69, v58, v59
	v_cvt_pk_bf16_f32 v70, v60, v61
	v_cvt_pk_bf16_f32 v71, v62, v63
	global_store_dwordx4 v82, v[64:67], s[16:17]
	global_store_dwordx4 v83, v[68:71], s[16:17]
	s_mov_b64 s[16:17], s[14:15]
	s_mov_b32 s26, s6
	s_mov_b32 s27, s13
	s_mov_b32 s4, s18
	s_cmpk_lt_u32 s4, 0x2300
	s_cbranch_scc0 .Ltr_drain
	s_branch .Ltr_loop

.LBB0_127:
	s_add_i32 s42, s16, s46
	s_cmpk_gt_i32 s42, 0xb27
	s_mov_b64 s[40:41], -1
	s_cbranch_scc1 .LBB0_126
	s_mul_hi_i32 s40, s42, 0x30c30c31
	s_lshr_b32 s41, s40, 31
	s_ashr_i32 s40, s40, 7
	s_add_i32 s54, s40, s41
	s_mul_i32 s40, s54, 0xfffffd60
	s_lshl_b32 s43, s54, 3
	s_add_i32 s41, s40, s42
	s_sub_i32 s40, 34, s43
	s_cmpk_gt_i32 s42, 0xa7f
	s_cselect_b32 s42, s40, 8
	s_abs_i32 s40, s42
	v_cvt_f32_u32_e32 v0, s40
	s_sub_i32 s50, 0, s40
	s_abs_i32 s44, s41
	s_xor_b32 s45, s41, s42
	v_rcp_iflag_f32_e32 v0, v0
	s_ashr_i32 s45, s45, 31
	v_mov_b32_e32 v8, v204
	v_mul_f32_e32 v0, 0x4f7ffffe, v0
	v_cvt_u32_f32_e32 v0, v0
	v_bfe_u32 v2, v8, 2, 4
	v_ashrrev_i32_e32 v1, 6, v8
	v_lshlrev_b32_e32 v3, 16, v1
	v_readfirstlane_b32 s51, v0
	s_mul_i32 s50, s50, s51
	s_mul_hi_u32 s50, s51, s50
	s_add_i32 s51, s51, s50
	s_mul_hi_u32 s50, s44, s51
	s_mul_i32 s51, s50, s40
	s_sub_i32 s44, s44, s51
	s_add_i32 s52, s50, 1
	s_sub_i32 s51, s44, s40
	s_cmp_ge_u32 s44, s40
	s_cselect_b32 s50, s52, s50
	s_cselect_b32 s44, s51, s44
	s_add_i32 s51, s50, 1
	s_cmp_ge_u32 s44, s40
	s_cselect_b32 s40, s51, s50
	s_xor_b32 s40, s40, s45
	s_sub_i32 s40, s40, s45
	s_mul_i32 s55, s42, s40
	s_add_i32 s41, s41, s43
	s_sub_i32 s42, s41, s55
	s_ashr_i32 s43, s42, 31
	s_lshl_b64 s[44:45], s[42:43], 20
	s_add_u32 s50, s23, s44
	s_addc_u32 s51, s28, s45
	s_ashr_i32 s41, s40, 31
	v_bfe_u32 v0, v8, 4, 2
	s_lshl_b64 s[44:45], s[40:41], 19
	v_bitop3_b32 v0, v0, v8, 3 bitop3:0x78
	s_mov_b32 s41, 0x1fffc0
	v_lshlrev_b32_e32 v9, 3, v0
	v_and_or_b32 v0, v8, s41, v2
	v_lshl_or_b32 v0, v0, 11, v9
	v_lshl_add_u32 v165, v1, 12, 32
	v_lshlrev_b32_e32 v1, 11, v1
	v_sub_u32_e32 v166, v165, v1
	v_ashrrev_i32_e32 v1, 31, v0
	v_readfirstlane_b32 s41, v165
	v_add_u32_e32 v12, 0x400, v165
	v_lshlrev_b32_e32 v10, 11, v2
	v_lshl_add_u64 v[0:1], v[0:1], 1, s[50:51]
	s_mov_b32 m0, s41
	v_readfirstlane_b32 s41, v12
	v_add_u32_e32 v12, 0x800, v165
	v_or3_b32 v2, v10, v3, v9
	global_load_lds_dwordx4 v[0:1], off
	v_lshl_add_u64 v[6:7], v[0:1], 0, s[6:7]
	s_mov_b32 m0, s41
	s_mov_b64 s[50:51], 0x20000
	v_readfirstlane_b32 s41, v12
	v_add_u32_e32 v12, 0xc00, v165
	s_add_u32 s52, s29, s44
	v_add_u32_e32 v11, 0x4000, v166
	v_ashrrev_i32_e32 v3, 31, v2
	global_load_lds_dwordx4 v[6:7], off
	v_lshl_add_u64 v[6:7], v[0:1], 0, s[50:51]
	s_mov_b32 m0, s41
	s_mov_b64 s[50:51], 0x30000
	v_readfirstlane_b32 s41, v12
	s_addc_u32 s53, s30, s45
	v_lshlrev_b64 v[2:3], 1, v[2:3]
	v_lshrrev_b32_e32 v240, 4, v10
	v_add_u32_e32 v2, v2, v240
	global_load_lds_dwordx4 v[6:7], off
	v_lshl_add_u64 v[6:7], v[0:1], 0, s[50:51]
	s_mov_b32 m0, s41
	v_readfirstlane_b32 s41, v11
	v_add_u32_e32 v11, 0x4400, v166
	v_lshl_add_u64 v[4:5], s[52:53], 0, v[2:3]
	global_load_lds_dwordx4 v[6:7], off
	s_mov_b32 m0, s41
	v_readfirstlane_b32 s41, v11
	v_add_u32_e32 v11, 0x6000, v165
	global_load_lds_dwordx4 v[4:5], off
	s_mov_b64 s[50:51], 0x10800
	v_lshl_add_u64 v[6:7], v[4:5], 0, s[50:51]
	s_mov_b32 m0, s41
	v_readfirstlane_b32 s41, v11
	v_add_u32_e32 v11, 0x6400, v165
	global_load_lds_dwordx4 v[6:7], off
	v_lshl_add_u64 v[6:7], v[0:1], 0, 64
	s_mov_b32 m0, s41
	v_readfirstlane_b32 s41, v11
	v_add_u32_e32 v11, 0x6800, v165
	global_load_lds_dwordx4 v[6:7], off
	v_lshl_add_u64 v[6:7], v[0:1], 0, s[8:9]
	s_mov_b32 m0, s41
	s_mov_b64 s[50:51], 0x20040
	v_readfirstlane_b32 s41, v11
	global_load_lds_dwordx4 v[6:7], off
	v_lshl_add_u64 v[6:7], v[0:1], 0, s[50:51]
	s_mov_b32 m0, s41
	s_mov_b64 s[50:51], 0x30040
	global_load_lds_dwordx4 v[6:7], off
	v_add_u32_e32 v6, 0x6c00, v165
	v_lshl_add_u64 v[0:1], v[0:1], 0, s[50:51]
	v_readfirstlane_b32 s41, v6
	v_add_u32_e32 v6, 0xa000, v166
	s_mov_b32 m0, s41
	v_readfirstlane_b32 s41, v6
	global_load_lds_dwordx4 v[0:1], off
	v_lshl_add_u64 v[0:1], v[4:5], 0, 64
	s_mov_b32 m0, s41
	s_add_u32 s44, s94, s44
	global_load_lds_dwordx4 v[0:1], off
	s_mov_b64 s[50:51], 0x10840
	v_lshl_add_u64 v[0:1], v[4:5], 0, s[50:51]
	v_add_u32_e32 v4, 0xa400, v166
	s_addc_u32 s45, s95, s45
	v_readfirstlane_b32 s41, v4
	s_mov_b32 m0, s41
	v_bfe_u32 v4, v8, 2, 2
	global_load_lds_dwordx4 v[0:1], off
	v_bfe_u32 v0, v8, 5, 1
	v_lshrrev_b32_e32 v1, 2, v8
	s_sub_i32 s41, s47, s55
	s_mulk_i32 s54, 0x298
	v_bitop3_b32 v1, v0, v1, 3 bitop3:0x78
	v_bitop3_b32 v0, v0, v4, 2 bitop3:0x36
	v_lshl_add_u64 v[130:131], s[44:45], 0, v[2:3]
	s_sub_i32 s44, s41, s54
	v_lshlrev_b32_e32 v128, 4, v0
	s_ashr_i32 s45, s44, 31
	v_lshlrev_b32_e32 v0, 11, v8
	s_lshl_b64 s[44:45], s[44:45], 20
	v_and_b32_e32 v0, 0xfffe0000, v0
	v_or3_b32 v0, v0, v10, v9
	s_add_u32 s44, s94, s44
	v_lshlrev_b32_e32 v167, 4, v1
	v_ashrrev_i32_e32 v1, 31, v0
	s_addc_u32 s45, s95, s45
	v_lshlrev_b32_e32 v5, 6, v8
	v_lshl_add_u64 v[132:133], v[0:1], 1, s[44:45]
	v_mov_b32_e32 v0, 0
	s_mov_b32 s49, 0
	v_and_b32_e32 v168, 0xffffe7c0, v5
	v_and_b32_e32 v169, 0x17c0, v5
	s_mov_b64 s[44:45], 0
	v_mov_b32_e32 v1, v0
	v_mov_b32_e32 v2, v0
	v_mov_b32_e32 v3, v0
	v_mov_b32_e32 v4, v0
	v_mov_b32_e32 v5, v0
	v_mov_b32_e32 v6, v0
	v_mov_b32_e32 v7, v0
	v_mov_b32_e32 v8, v0
	v_mov_b32_e32 v9, v0
	v_mov_b32_e32 v10, v0
	v_mov_b32_e32 v11, v0
	v_mov_b32_e32 v12, v0
	v_mov_b32_e32 v13, v0
	v_mov_b32_e32 v14, v0
	v_mov_b32_e32 v15, v0
	v_mov_b32_e32 v16, v0
	v_mov_b32_e32 v17, v0
	v_mov_b32_e32 v18, v0
	v_mov_b32_e32 v19, v0
	v_mov_b32_e32 v20, v0
	v_mov_b32_e32 v21, v0
	v_mov_b32_e32 v22, v0
	v_mov_b32_e32 v23, v0
	v_mov_b32_e32 v24, v0
	v_mov_b32_e32 v25, v0
	v_mov_b32_e32 v26, v0
	v_mov_b32_e32 v27, v0
	v_mov_b32_e32 v28, v0
	v_mov_b32_e32 v29, v0
	v_mov_b32_e32 v30, v0
	v_mov_b32_e32 v31, v0
	v_mov_b32_e32 v32, v0
	v_mov_b32_e32 v33, v0
	v_mov_b32_e32 v34, v0
	v_mov_b32_e32 v35, v0
	v_mov_b32_e32 v36, v0
	v_mov_b32_e32 v37, v0
	v_mov_b32_e32 v38, v0
	v_mov_b32_e32 v39, v0
	v_mov_b32_e32 v40, v0
	v_mov_b32_e32 v41, v0
	v_mov_b32_e32 v42, v0
	v_mov_b32_e32 v43, v0
	v_mov_b32_e32 v44, v0
	v_mov_b32_e32 v45, v0
	v_mov_b32_e32 v46, v0
	v_mov_b32_e32 v47, v0
	v_mov_b32_e32 v48, v0
	v_mov_b32_e32 v49, v0
	v_mov_b32_e32 v50, v0
	v_mov_b32_e32 v51, v0
	v_mov_b32_e32 v52, v0
	v_mov_b32_e32 v53, v0
	v_mov_b32_e32 v54, v0
	v_mov_b32_e32 v55, v0
	v_mov_b32_e32 v56, v0
	v_mov_b32_e32 v57, v0
	v_mov_b32_e32 v58, v0
	v_mov_b32_e32 v59, v0
	v_mov_b32_e32 v60, v0
	v_mov_b32_e32 v61, v0
	v_mov_b32_e32 v62, v0
	v_mov_b32_e32 v63, v0
	v_mov_b32_e32 v64, v0
	v_mov_b32_e32 v65, v0
	v_mov_b32_e32 v66, v0
	v_mov_b32_e32 v67, v0
	v_mov_b32_e32 v68, v0
	v_mov_b32_e32 v69, v0
	v_mov_b32_e32 v70, v0
	v_mov_b32_e32 v71, v0
	v_mov_b32_e32 v72, v0
	v_mov_b32_e32 v73, v0
	v_mov_b32_e32 v74, v0
	v_mov_b32_e32 v75, v0
	v_mov_b32_e32 v76, v0
	v_mov_b32_e32 v77, v0
	v_mov_b32_e32 v78, v0
	v_mov_b32_e32 v79, v0
	v_mov_b32_e32 v80, v0
	v_mov_b32_e32 v81, v0
	v_mov_b32_e32 v82, v0
	v_mov_b32_e32 v83, v0
	v_mov_b32_e32 v84, v0
	v_mov_b32_e32 v85, v0
	v_mov_b32_e32 v86, v0
	v_mov_b32_e32 v87, v0
	v_mov_b32_e32 v88, v0
	v_mov_b32_e32 v89, v0
	v_mov_b32_e32 v90, v0
	v_mov_b32_e32 v91, v0
	v_mov_b32_e32 v92, v0
	v_mov_b32_e32 v93, v0
	v_mov_b32_e32 v94, v0
	v_mov_b32_e32 v95, v0
	v_mov_b32_e32 v96, v0
	v_mov_b32_e32 v97, v0
	v_mov_b32_e32 v98, v0
	v_mov_b32_e32 v99, v0
	v_mov_b32_e32 v100, v0
	v_mov_b32_e32 v101, v0
	v_mov_b32_e32 v102, v0
	v_mov_b32_e32 v103, v0
	v_mov_b32_e32 v104, v0
	v_mov_b32_e32 v105, v0
	v_mov_b32_e32 v106, v0
	v_mov_b32_e32 v107, v0
	v_mov_b32_e32 v108, v0
	v_mov_b32_e32 v109, v0
	v_mov_b32_e32 v110, v0
	v_mov_b32_e32 v111, v0
	v_mov_b32_e32 v112, v0
	v_mov_b32_e32 v113, v0
	v_mov_b32_e32 v114, v0
	v_mov_b32_e32 v115, v0
	v_mov_b32_e32 v116, v0
	v_mov_b32_e32 v117, v0
	v_mov_b32_e32 v118, v0
	v_mov_b32_e32 v119, v0
	v_mov_b32_e32 v120, v0
	v_mov_b32_e32 v121, v0
	v_mov_b32_e32 v122, v0
	v_mov_b32_e32 v123, v0
	v_mov_b32_e32 v124, v0
	v_mov_b32_e32 v125, v0
	v_mov_b32_e32 v126, v0
	v_mov_b32_e32 v127, v0
	v_add3_u32 v230, v168, v167, 32
	v_add3_u32 v231, v168, v128, 32
	v_add_u32_e32 v232, 0x4020, v169
	v_add_u32_e32 v233, v232, v128
	v_add_u32_e32 v232, v232, v167
	v_subrev_u32_e32 v234, s94, v132
	v_subrev_u32_e32 v238, s94, v130
	v_add_u32_e32 v234, 0x15c88080, v234
	v_sub_u32_e32 v238, v238, v240
	v_add_u32_e32 v238, 0x13288000, v238
	v_add_u32_e32 v235, 0x10000, v234
	v_add_u32_e32 v236, 0x20000, v234
	v_add_u32_e32 v237, 0x30000, v234
	v_add_u32_e32 v239, 0x10000, v238
	v_readfirstlane_b32 s101, v165
	v_readfirstlane_b32 s49, v166
	s_mov_b64 s[98:99], s[94:95]
	s_add_u32 s44, s94, 64
	s_addc_u32 s45, s95, 0
	s_add_u32 s49, s49, 0x4000
	s_movk_i32 s36, 0x80
	s_movk_i32 s37, 0x880
	s_waitcnt vmcnt(6)
	s_barrier
	ds_read_b128 v[170:173], v232 offset:0
	ds_read_b128 v[174:177], v232 offset:2048
	ds_read_b128 v[178:181], v230 offset:0
	ds_read_b128 v[182:185], v230 offset:2048
	ds_read_b128 v[186:189], v230 offset:4096
	ds_read_b128 v[190:193], v230 offset:6144
	s_waitcnt lgkmcnt(2)
	s_setprio 1
	v_mfma_f32_32x32x16_bf16 v[112:127], v[178:181], v[170:173], v[112:127]
	v_mfma_f32_32x32x16_bf16 v[96:111], v[178:181], v[174:177], v[96:111]
	v_mfma_f32_32x32x16_bf16 v[80:95], v[182:185], v[170:173], v[80:95]
	v_mfma_f32_32x32x16_bf16 v[64:79], v[182:185], v[174:177], v[64:79]
	s_setprio 0
	ds_read_b128 v[206:209], v233 offset:0
	ds_read_b128 v[210:213], v233 offset:2048
	ds_read_b128 v[214:217], v231 offset:0
	ds_read_b128 v[218:221], v231 offset:2048
	s_waitcnt lgkmcnt(4)
	s_setprio 1
	v_mfma_f32_32x32x16_bf16 v[48:63], v[186:189], v[170:173], v[48:63]
	v_mfma_f32_32x32x16_bf16 v[32:47], v[186:189], v[174:177], v[32:47]
	v_mfma_f32_32x32x16_bf16 v[16:31], v[190:193], v[170:173], v[16:31]
	v_mfma_f32_32x32x16_bf16 v[0:15], v[190:193], v[174:177], v[0:15]
	s_setprio 0
	ds_read_b128 v[222:225], v231 offset:4096
	ds_read_b128 v[226:229], v231 offset:6144
	s_waitcnt lgkmcnt(2)
	s_setprio 1
	v_mfma_f32_32x32x16_bf16 v[112:127], v[214:217], v[206:209], v[112:127]
	v_mfma_f32_32x32x16_bf16 v[96:111], v[214:217], v[210:213], v[96:111]
	v_mfma_f32_32x32x16_bf16 v[80:95], v[218:221], v[206:209], v[80:95]
	v_mfma_f32_32x32x16_bf16 v[64:79], v[218:221], v[210:213], v[64:79]
	s_setprio 0
	s_mov_b32 s100, 10
.Lp1m_kloop:
	s_waitcnt vmcnt(0) lgkmcnt(0)
	s_barrier
	ds_read_b128 v[170:173], v232 offset:24576
	ds_read_b128 v[174:177], v232 offset:26624
	ds_read_b128 v[178:181], v230 offset:24576
	ds_read_b128 v[182:185], v230 offset:26624
	ds_read_b128 v[186:189], v230 offset:28672
	ds_read_b128 v[190:193], v230 offset:30720
	s_setprio 1
	v_mfma_f32_32x32x16_bf16 v[48:63], v[222:225], v[206:209], v[48:63]
	v_mfma_f32_32x32x16_bf16 v[32:47], v[222:225], v[210:213], v[32:47]
	v_mfma_f32_32x32x16_bf16 v[16:31], v[226:229], v[206:209], v[16:31]
	v_mfma_f32_32x32x16_bf16 v[0:15], v[226:229], v[210:213], v[0:15]
	s_setprio 0
	s_add_u32 m0, s101, 0xc000
	s_nop 0
	global_load_lds_dwordx4 v234, s[98:99]
	s_add_u32 m0, s101, 0x0
	s_nop 0
	global_load_lds_dwordx4 v234, s[44:45]
	s_add_u32 m0, s101, 0xc400
	s_nop 0
	global_load_lds_dwordx4 v235, s[98:99]
	s_add_u32 m0, s101, 0x400
	s_nop 0
	global_load_lds_dwordx4 v235, s[44:45]
	s_waitcnt lgkmcnt(2)
	s_setprio 1
	v_mfma_f32_32x32x16_bf16 v[112:127], v[178:181], v[170:173], v[112:127]
	v_mfma_f32_32x32x16_bf16 v[96:111], v[178:181], v[174:177], v[96:111]
	v_mfma_f32_32x32x16_bf16 v[80:95], v[182:185], v[170:173], v[80:95]
	v_mfma_f32_32x32x16_bf16 v[64:79], v[182:185], v[174:177], v[64:79]
	s_setprio 0
	ds_read_b128 v[206:209], v233 offset:24576
	ds_read_b128 v[210:213], v233 offset:26624
	ds_read_b128 v[214:217], v231 offset:24576
	ds_read_b128 v[218:221], v231 offset:26624
	s_add_u32 m0, s101, 0xc800
	s_nop 0
	global_load_lds_dwordx4 v236, s[98:99]
	s_add_u32 m0, s101, 0x800
	s_nop 0
	global_load_lds_dwordx4 v236, s[44:45]
	s_add_u32 m0, s101, 0xcc00
	s_nop 0
	global_load_lds_dwordx4 v237, s[98:99]
	s_add_u32 m0, s101, 0xc00
	s_nop 0
	global_load_lds_dwordx4 v237, s[44:45]
	s_waitcnt lgkmcnt(4)
	s_setprio 1
	v_mfma_f32_32x32x16_bf16 v[48:63], v[186:189], v[170:173], v[48:63]
	v_mfma_f32_32x32x16_bf16 v[32:47], v[186:189], v[174:177], v[32:47]
	v_mfma_f32_32x32x16_bf16 v[16:31], v[190:193], v[170:173], v[16:31]
	v_mfma_f32_32x32x16_bf16 v[0:15], v[190:193], v[174:177], v[0:15]
	s_setprio 0
	ds_read_b128 v[222:225], v231 offset:28672
	ds_read_b128 v[226:229], v231 offset:30720
	v_xad_u32 v241, s36, v240, v238
	v_xad_u32 v242, s37, v240, v239
	s_add_u32 m0, s49, 0xc000
	s_nop 0
	global_load_lds_dwordx4 v241, s[94:95]
	s_add_u32 m0, s49, 0xffffffc0
	s_nop 0
	global_load_lds_dwordx4 v241, s[94:95] offset:64
	s_add_u32 m0, s49, 0xc400
	s_nop 0
	global_load_lds_dwordx4 v242, s[94:95]
	s_add_u32 m0, s49, 0x3c0
	s_nop 0
	global_load_lds_dwordx4 v242, s[94:95] offset:64
	s_add_u32 s36, s36, 0x80
	s_xor_b32 s37, s36, 0x800
	s_add_u32 s98, s98, 128
	s_addc_u32 s99, s99, 0
	s_add_u32 s44, s44, 128
	s_addc_u32 s45, s45, 0
	s_waitcnt lgkmcnt(2)
	s_setprio 1
	v_mfma_f32_32x32x16_bf16 v[112:127], v[214:217], v[206:209], v[112:127]
	v_mfma_f32_32x32x16_bf16 v[96:111], v[214:217], v[210:213], v[96:111]
	v_mfma_f32_32x32x16_bf16 v[80:95], v[218:221], v[206:209], v[80:95]
	v_mfma_f32_32x32x16_bf16 v[64:79], v[218:221], v[210:213], v[64:79]
	s_setprio 0
	s_waitcnt vmcnt(0) lgkmcnt(0)
	s_barrier
	ds_read_b128 v[170:173], v232 offset:49152
	ds_read_b128 v[174:177], v232 offset:51200
	ds_read_b128 v[178:181], v230 offset:49152
	ds_read_b128 v[182:185], v230 offset:51200
	ds_read_b128 v[186:189], v230 offset:53248
	ds_read_b128 v[190:193], v230 offset:55296
	s_setprio 1
	v_mfma_f32_32x32x16_bf16 v[48:63], v[222:225], v[206:209], v[48:63]
	v_mfma_f32_32x32x16_bf16 v[32:47], v[222:225], v[210:213], v[32:47]
	v_mfma_f32_32x32x16_bf16 v[16:31], v[226:229], v[206:209], v[16:31]
	v_mfma_f32_32x32x16_bf16 v[0:15], v[226:229], v[210:213], v[0:15]
	s_setprio 0
	s_waitcnt lgkmcnt(2)
	s_setprio 1
	v_mfma_f32_32x32x16_bf16 v[112:127], v[178:181], v[170:173], v[112:127]
	v_mfma_f32_32x32x16_bf16 v[96:111], v[178:181], v[174:177], v[96:111]
	v_mfma_f32_32x32x16_bf16 v[80:95], v[182:185], v[170:173], v[80:95]
	v_mfma_f32_32x32x16_bf16 v[64:79], v[182:185], v[174:177], v[64:79]
	s_setprio 0
	ds_read_b128 v[206:209], v233 offset:49152
	ds_read_b128 v[210:213], v233 offset:51200
	ds_read_b128 v[214:217], v231 offset:49152
	ds_read_b128 v[218:221], v231 offset:51200
	s_waitcnt lgkmcnt(4)
	s_setprio 1
	v_mfma_f32_32x32x16_bf16 v[48:63], v[186:189], v[170:173], v[48:63]
	v_mfma_f32_32x32x16_bf16 v[32:47], v[186:189], v[174:177], v[32:47]
	v_mfma_f32_32x32x16_bf16 v[16:31], v[190:193], v[170:173], v[16:31]
	v_mfma_f32_32x32x16_bf16 v[0:15], v[190:193], v[174:177], v[0:15]
	s_setprio 0
	ds_read_b128 v[222:225], v231 offset:53248
	ds_read_b128 v[226:229], v231 offset:55296
	s_waitcnt lgkmcnt(2)
	s_setprio 1
	v_mfma_f32_32x32x16_bf16 v[112:127], v[214:217], v[206:209], v[112:127]
	v_mfma_f32_32x32x16_bf16 v[96:111], v[214:217], v[210:213], v[96:111]
	v_mfma_f32_32x32x16_bf16 v[80:95], v[218:221], v[206:209], v[80:95]
	v_mfma_f32_32x32x16_bf16 v[64:79], v[218:221], v[210:213], v[64:79]
	s_setprio 0
	s_waitcnt vmcnt(0) lgkmcnt(0)
	s_barrier
	ds_read_b128 v[170:173], v232 offset:0
	ds_read_b128 v[174:177], v232 offset:2048
	ds_read_b128 v[178:181], v230 offset:0
	ds_read_b128 v[182:185], v230 offset:2048
	ds_read_b128 v[186:189], v230 offset:4096
	ds_read_b128 v[190:193], v230 offset:6144
	s_setprio 1
	v_mfma_f32_32x32x16_bf16 v[48:63], v[222:225], v[206:209], v[48:63]
	v_mfma_f32_32x32x16_bf16 v[32:47], v[222:225], v[210:213], v[32:47]
	v_mfma_f32_32x32x16_bf16 v[16:31], v[226:229], v[206:209], v[16:31]
	v_mfma_f32_32x32x16_bf16 v[0:15], v[226:229], v[210:213], v[0:15]
	s_setprio 0
	s_add_u32 m0, s101, 0x6000
	s_nop 0
	global_load_lds_dwordx4 v234, s[98:99]
	s_add_u32 m0, s101, 0xc000
	s_nop 0
	global_load_lds_dwordx4 v234, s[44:45]
	s_add_u32 m0, s101, 0x6400
	s_nop 0
	global_load_lds_dwordx4 v235, s[98:99]
	s_add_u32 m0, s101, 0xc400
	s_nop 0
	global_load_lds_dwordx4 v235, s[44:45]
	s_waitcnt lgkmcnt(2)
	s_setprio 1
	v_mfma_f32_32x32x16_bf16 v[112:127], v[178:181], v[170:173], v[112:127]
	v_mfma_f32_32x32x16_bf16 v[96:111], v[178:181], v[174:177], v[96:111]
	v_mfma_f32_32x32x16_bf16 v[80:95], v[182:185], v[170:173], v[80:95]
	v_mfma_f32_32x32x16_bf16 v[64:79], v[182:185], v[174:177], v[64:79]
	s_setprio 0
	ds_read_b128 v[206:209], v233 offset:0
	ds_read_b128 v[210:213], v233 offset:2048
	ds_read_b128 v[214:217], v231 offset:0
	ds_read_b128 v[218:221], v231 offset:2048
	s_add_u32 m0, s101, 0x6800
	s_nop 0
	global_load_lds_dwordx4 v236, s[98:99]
	s_add_u32 m0, s101, 0xc800
	s_nop 0
	global_load_lds_dwordx4 v236, s[44:45]
	s_add_u32 m0, s101, 0x6c00
	s_nop 0
	global_load_lds_dwordx4 v237, s[98:99]
	s_add_u32 m0, s101, 0xcc00
	s_nop 0
	global_load_lds_dwordx4 v237, s[44:45]
	s_waitcnt lgkmcnt(4)
	s_setprio 1
	v_mfma_f32_32x32x16_bf16 v[48:63], v[186:189], v[170:173], v[48:63]
	v_mfma_f32_32x32x16_bf16 v[32:47], v[186:189], v[174:177], v[32:47]
	v_mfma_f32_32x32x16_bf16 v[16:31], v[190:193], v[170:173], v[16:31]
	v_mfma_f32_32x32x16_bf16 v[0:15], v[190:193], v[174:177], v[0:15]
	s_setprio 0
	ds_read_b128 v[222:225], v231 offset:4096
	ds_read_b128 v[226:229], v231 offset:6144
	v_xad_u32 v241, s36, v240, v238
	v_xad_u32 v242, s37, v240, v239
	s_add_u32 m0, s49, 0x6000
	s_nop 0
	global_load_lds_dwordx4 v241, s[94:95]
	s_add_u32 m0, s49, 0xbfc0
	s_nop 0
	global_load_lds_dwordx4 v241, s[94:95] offset:64
	s_add_u32 m0, s49, 0x6400
	s_nop 0
	global_load_lds_dwordx4 v242, s[94:95]
	s_add_u32 m0, s49, 0xc3c0
	s_nop 0
	global_load_lds_dwordx4 v242, s[94:95] offset:64
	s_add_u32 s36, s36, 0x80
	s_xor_b32 s37, s36, 0x800
	s_add_u32 s98, s98, 128
	s_addc_u32 s99, s99, 0
	s_add_u32 s44, s44, 128
	s_addc_u32 s45, s45, 0
	s_waitcnt lgkmcnt(2)
	s_setprio 1
	v_mfma_f32_32x32x16_bf16 v[112:127], v[214:217], v[206:209], v[112:127]
	v_mfma_f32_32x32x16_bf16 v[96:111], v[214:217], v[210:213], v[96:111]
	v_mfma_f32_32x32x16_bf16 v[80:95], v[218:221], v[206:209], v[80:95]
	v_mfma_f32_32x32x16_bf16 v[64:79], v[218:221], v[210:213], v[64:79]
	s_setprio 0
	s_waitcnt vmcnt(0) lgkmcnt(0)
	s_barrier
	ds_read_b128 v[170:173], v232 offset:24576
	ds_read_b128 v[174:177], v232 offset:26624
	ds_read_b128 v[178:181], v230 offset:24576
	ds_read_b128 v[182:185], v230 offset:26624
	ds_read_b128 v[186:189], v230 offset:28672
	ds_read_b128 v[190:193], v230 offset:30720
	s_setprio 1
	v_mfma_f32_32x32x16_bf16 v[48:63], v[222:225], v[206:209], v[48:63]
	v_mfma_f32_32x32x16_bf16 v[32:47], v[222:225], v[210:213], v[32:47]
	v_mfma_f32_32x32x16_bf16 v[16:31], v[226:229], v[206:209], v[16:31]
	v_mfma_f32_32x32x16_bf16 v[0:15], v[226:229], v[210:213], v[0:15]
	s_setprio 0
	s_waitcnt lgkmcnt(2)
	s_setprio 1
	v_mfma_f32_32x32x16_bf16 v[112:127], v[178:181], v[170:173], v[112:127]
	v_mfma_f32_32x32x16_bf16 v[96:111], v[178:181], v[174:177], v[96:111]
	v_mfma_f32_32x32x16_bf16 v[80:95], v[182:185], v[170:173], v[80:95]
	v_mfma_f32_32x32x16_bf16 v[64:79], v[182:185], v[174:177], v[64:79]
	s_setprio 0
	ds_read_b128 v[206:209], v233 offset:24576
	ds_read_b128 v[210:213], v233 offset:26624
	ds_read_b128 v[214:217], v231 offset:24576
	ds_read_b128 v[218:221], v231 offset:26624
	s_waitcnt lgkmcnt(4)
	s_setprio 1
	v_mfma_f32_32x32x16_bf16 v[48:63], v[186:189], v[170:173], v[48:63]
	v_mfma_f32_32x32x16_bf16 v[32:47], v[186:189], v[174:177], v[32:47]
	v_mfma_f32_32x32x16_bf16 v[16:31], v[190:193], v[170:173], v[16:31]
	v_mfma_f32_32x32x16_bf16 v[0:15], v[190:193], v[174:177], v[0:15]
	s_setprio 0
	ds_read_b128 v[222:225], v231 offset:28672
	ds_read_b128 v[226:229], v231 offset:30720
	s_waitcnt lgkmcnt(2)
	s_setprio 1
	v_mfma_f32_32x32x16_bf16 v[112:127], v[214:217], v[206:209], v[112:127]
	v_mfma_f32_32x32x16_bf16 v[96:111], v[214:217], v[210:213], v[96:111]
	v_mfma_f32_32x32x16_bf16 v[80:95], v[218:221], v[206:209], v[80:95]
	v_mfma_f32_32x32x16_bf16 v[64:79], v[218:221], v[210:213], v[64:79]
	s_setprio 0
	s_waitcnt vmcnt(0) lgkmcnt(0)
	s_barrier
	ds_read_b128 v[170:173], v232 offset:49152
	ds_read_b128 v[174:177], v232 offset:51200
	ds_read_b128 v[178:181], v230 offset:49152
	ds_read_b128 v[182:185], v230 offset:51200
	ds_read_b128 v[186:189], v230 offset:53248
	ds_read_b128 v[190:193], v230 offset:55296
	s_setprio 1
	v_mfma_f32_32x32x16_bf16 v[48:63], v[222:225], v[206:209], v[48:63]
	v_mfma_f32_32x32x16_bf16 v[32:47], v[222:225], v[210:213], v[32:47]
	v_mfma_f32_32x32x16_bf16 v[16:31], v[226:229], v[206:209], v[16:31]
	v_mfma_f32_32x32x16_bf16 v[0:15], v[226:229], v[210:213], v[0:15]
	s_setprio 0
	s_add_u32 m0, s101, 0x0
	s_nop 0
	global_load_lds_dwordx4 v234, s[98:99]
	s_add_u32 m0, s101, 0x6000
	s_nop 0
	global_load_lds_dwordx4 v234, s[44:45]
	s_add_u32 m0, s101, 0x400
	s_nop 0
	global_load_lds_dwordx4 v235, s[98:99]
	s_add_u32 m0, s101, 0x6400
	s_nop 0
	global_load_lds_dwordx4 v235, s[44:45]
	s_waitcnt lgkmcnt(2)
	s_setprio 1
	v_mfma_f32_32x32x16_bf16 v[112:127], v[178:181], v[170:173], v[112:127]
	v_mfma_f32_32x32x16_bf16 v[96:111], v[178:181], v[174:177], v[96:111]
	v_mfma_f32_32x32x16_bf16 v[80:95], v[182:185], v[170:173], v[80:95]
	v_mfma_f32_32x32x16_bf16 v[64:79], v[182:185], v[174:177], v[64:79]
	s_setprio 0
	ds_read_b128 v[206:209], v233 offset:49152
	ds_read_b128 v[210:213], v233 offset:51200
	ds_read_b128 v[214:217], v231 offset:49152
	ds_read_b128 v[218:221], v231 offset:51200
	s_add_u32 m0, s101, 0x800
	s_nop 0
	global_load_lds_dwordx4 v236, s[98:99]
	s_add_u32 m0, s101, 0x6800
	s_nop 0
	global_load_lds_dwordx4 v236, s[44:45]
	s_add_u32 m0, s101, 0xc00
	s_nop 0
	global_load_lds_dwordx4 v237, s[98:99]
	s_add_u32 m0, s101, 0x6c00
	s_nop 0
	global_load_lds_dwordx4 v237, s[44:45]
	s_waitcnt lgkmcnt(4)
	s_setprio 1
	v_mfma_f32_32x32x16_bf16 v[48:63], v[186:189], v[170:173], v[48:63]
	v_mfma_f32_32x32x16_bf16 v[32:47], v[186:189], v[174:177], v[32:47]
	v_mfma_f32_32x32x16_bf16 v[16:31], v[190:193], v[170:173], v[16:31]
	v_mfma_f32_32x32x16_bf16 v[0:15], v[190:193], v[174:177], v[0:15]
	s_setprio 0
	ds_read_b128 v[222:225], v231 offset:53248
	ds_read_b128 v[226:229], v231 offset:55296
	v_xad_u32 v241, s36, v240, v238
	v_xad_u32 v242, s37, v240, v239
	s_add_u32 m0, s49, 0x0
	s_nop 0
	global_load_lds_dwordx4 v241, s[94:95]
	s_add_u32 m0, s49, 0x5fc0
	s_nop 0
	global_load_lds_dwordx4 v241, s[94:95] offset:64
	s_add_u32 m0, s49, 0x400
	s_nop 0
	global_load_lds_dwordx4 v242, s[94:95]
	s_add_u32 m0, s49, 0x63c0
	s_nop 0
	global_load_lds_dwordx4 v242, s[94:95] offset:64
	s_add_u32 s36, s36, 0x80
	s_xor_b32 s37, s36, 0x800
	s_add_u32 s98, s98, 128
	s_addc_u32 s99, s99, 0
	s_add_u32 s44, s44, 128
	s_addc_u32 s45, s45, 0
	s_waitcnt lgkmcnt(2)
	s_setprio 1
	v_mfma_f32_32x32x16_bf16 v[112:127], v[214:217], v[206:209], v[112:127]
	v_mfma_f32_32x32x16_bf16 v[96:111], v[214:217], v[210:213], v[96:111]
	v_mfma_f32_32x32x16_bf16 v[80:95], v[218:221], v[206:209], v[80:95]
	v_mfma_f32_32x32x16_bf16 v[64:79], v[218:221], v[210:213], v[64:79]
	s_setprio 0
	s_waitcnt vmcnt(0) lgkmcnt(0)
	s_barrier
	ds_read_b128 v[170:173], v232 offset:0
	ds_read_b128 v[174:177], v232 offset:2048
	ds_read_b128 v[178:181], v230 offset:0
	ds_read_b128 v[182:185], v230 offset:2048
	ds_read_b128 v[186:189], v230 offset:4096
	ds_read_b128 v[190:193], v230 offset:6144
	s_setprio 1
	v_mfma_f32_32x32x16_bf16 v[48:63], v[222:225], v[206:209], v[48:63]
	v_mfma_f32_32x32x16_bf16 v[32:47], v[222:225], v[210:213], v[32:47]
	v_mfma_f32_32x32x16_bf16 v[16:31], v[226:229], v[206:209], v[16:31]
	v_mfma_f32_32x32x16_bf16 v[0:15], v[226:229], v[210:213], v[0:15]
	s_setprio 0
	s_waitcnt lgkmcnt(2)
	s_setprio 1
	v_mfma_f32_32x32x16_bf16 v[112:127], v[178:181], v[170:173], v[112:127]
	v_mfma_f32_32x32x16_bf16 v[96:111], v[178:181], v[174:177], v[96:111]
	v_mfma_f32_32x32x16_bf16 v[80:95], v[182:185], v[170:173], v[80:95]
	v_mfma_f32_32x32x16_bf16 v[64:79], v[182:185], v[174:177], v[64:79]
	s_setprio 0
	ds_read_b128 v[206:209], v233 offset:0
	ds_read_b128 v[210:213], v233 offset:2048
	ds_read_b128 v[214:217], v231 offset:0
	ds_read_b128 v[218:221], v231 offset:2048
	s_waitcnt lgkmcnt(4)
	s_setprio 1
	v_mfma_f32_32x32x16_bf16 v[48:63], v[186:189], v[170:173], v[48:63]
	v_mfma_f32_32x32x16_bf16 v[32:47], v[186:189], v[174:177], v[32:47]
	v_mfma_f32_32x32x16_bf16 v[16:31], v[190:193], v[170:173], v[16:31]
	v_mfma_f32_32x32x16_bf16 v[0:15], v[190:193], v[174:177], v[0:15]
	s_setprio 0
	ds_read_b128 v[222:225], v231 offset:4096
	ds_read_b128 v[226:229], v231 offset:6144
	s_waitcnt lgkmcnt(2)
	s_setprio 1
	v_mfma_f32_32x32x16_bf16 v[112:127], v[214:217], v[206:209], v[112:127]
	v_mfma_f32_32x32x16_bf16 v[96:111], v[214:217], v[210:213], v[96:111]
	v_mfma_f32_32x32x16_bf16 v[80:95], v[218:221], v[206:209], v[80:95]
	v_mfma_f32_32x32x16_bf16 v[64:79], v[218:221], v[210:213], v[64:79]
	s_setprio 0
	s_sub_u32 s100, s100, 1
	s_cmp_lg_u32 s100, 0
	s_cbranch_scc1 .Lp1m_kloop
	s_waitcnt vmcnt(0) lgkmcnt(0)
	s_barrier
	ds_read_b128 v[170:173], v232 offset:24576
	ds_read_b128 v[174:177], v232 offset:26624
	ds_read_b128 v[178:181], v230 offset:24576
	ds_read_b128 v[182:185], v230 offset:26624
	ds_read_b128 v[186:189], v230 offset:28672
	ds_read_b128 v[190:193], v230 offset:30720
	s_setprio 1
	v_mfma_f32_32x32x16_bf16 v[48:63], v[222:225], v[206:209], v[48:63]
	v_mfma_f32_32x32x16_bf16 v[32:47], v[222:225], v[210:213], v[32:47]
	v_mfma_f32_32x32x16_bf16 v[16:31], v[226:229], v[206:209], v[16:31]
	v_mfma_f32_32x32x16_bf16 v[0:15], v[226:229], v[210:213], v[0:15]
	s_setprio 0
	s_add_u32 m0, s101, 0xc000
	s_nop 0
	global_load_lds_dwordx4 v234, s[98:99]
	s_add_u32 m0, s101, 0x0
	s_nop 0
	global_load_lds_dwordx4 v234, s[44:45]
	s_add_u32 m0, s101, 0xc400
	s_nop 0
	global_load_lds_dwordx4 v235, s[98:99]
	s_add_u32 m0, s101, 0x400
	s_nop 0
	global_load_lds_dwordx4 v235, s[44:45]
	s_waitcnt lgkmcnt(2)
	s_setprio 1
	v_mfma_f32_32x32x16_bf16 v[112:127], v[178:181], v[170:173], v[112:127]
	v_mfma_f32_32x32x16_bf16 v[96:111], v[178:181], v[174:177], v[96:111]
	v_mfma_f32_32x32x16_bf16 v[80:95], v[182:185], v[170:173], v[80:95]
	v_mfma_f32_32x32x16_bf16 v[64:79], v[182:185], v[174:177], v[64:79]
	s_setprio 0
	ds_read_b128 v[206:209], v233 offset:24576
	ds_read_b128 v[210:213], v233 offset:26624
	ds_read_b128 v[214:217], v231 offset:24576
	ds_read_b128 v[218:221], v231 offset:26624
	s_add_u32 m0, s101, 0xc800
	s_nop 0
	global_load_lds_dwordx4 v236, s[98:99]
	s_add_u32 m0, s101, 0x800
	s_nop 0
	global_load_lds_dwordx4 v236, s[44:45]
	s_add_u32 m0, s101, 0xcc00
	s_nop 0
	global_load_lds_dwordx4 v237, s[98:99]
	s_add_u32 m0, s101, 0xc00
	s_nop 0
	global_load_lds_dwordx4 v237, s[44:45]
	s_waitcnt lgkmcnt(4)
	s_setprio 1
	v_mfma_f32_32x32x16_bf16 v[48:63], v[186:189], v[170:173], v[48:63]
	v_mfma_f32_32x32x16_bf16 v[32:47], v[186:189], v[174:177], v[32:47]
	v_mfma_f32_32x32x16_bf16 v[16:31], v[190:193], v[170:173], v[16:31]
	v_mfma_f32_32x32x16_bf16 v[0:15], v[190:193], v[174:177], v[0:15]
	s_setprio 0
	ds_read_b128 v[222:225], v231 offset:28672
	ds_read_b128 v[226:229], v231 offset:30720
	v_xad_u32 v241, s36, v240, v238
	v_xad_u32 v242, s37, v240, v239
	s_add_u32 m0, s49, 0xc000
	s_nop 0
	global_load_lds_dwordx4 v241, s[94:95]
	s_add_u32 m0, s49, 0xffffffc0
	s_nop 0
	global_load_lds_dwordx4 v241, s[94:95] offset:64
	s_add_u32 m0, s49, 0xc400
	s_nop 0
	global_load_lds_dwordx4 v242, s[94:95]
	s_add_u32 m0, s49, 0x3c0
	s_nop 0
	global_load_lds_dwordx4 v242, s[94:95] offset:64
	s_add_u32 s36, s36, 0x80
	s_xor_b32 s37, s36, 0x800
	s_add_u32 s98, s98, 128
	s_addc_u32 s99, s99, 0
	s_add_u32 s44, s44, 128
	s_addc_u32 s45, s45, 0
	s_waitcnt lgkmcnt(2)
	s_setprio 1
	v_mfma_f32_32x32x16_bf16 v[112:127], v[214:217], v[206:209], v[112:127]
	v_mfma_f32_32x32x16_bf16 v[96:111], v[214:217], v[210:213], v[96:111]
	v_mfma_f32_32x32x16_bf16 v[80:95], v[218:221], v[206:209], v[80:95]
	v_mfma_f32_32x32x16_bf16 v[64:79], v[218:221], v[210:213], v[64:79]
	s_setprio 0
	s_waitcnt vmcnt(0) lgkmcnt(0)
	s_barrier
	ds_read_b128 v[170:173], v232 offset:49152
	ds_read_b128 v[174:177], v232 offset:51200
	ds_read_b128 v[178:181], v230 offset:49152
	ds_read_b128 v[182:185], v230 offset:51200
	ds_read_b128 v[186:189], v230 offset:53248
	ds_read_b128 v[190:193], v230 offset:55296
	s_setprio 1
	v_mfma_f32_32x32x16_bf16 v[48:63], v[222:225], v[206:209], v[48:63]
	v_mfma_f32_32x32x16_bf16 v[32:47], v[222:225], v[210:213], v[32:47]
	v_mfma_f32_32x32x16_bf16 v[16:31], v[226:229], v[206:209], v[16:31]
	v_mfma_f32_32x32x16_bf16 v[0:15], v[226:229], v[210:213], v[0:15]
	s_setprio 0
	s_waitcnt lgkmcnt(2)
	s_setprio 1
	v_mfma_f32_32x32x16_bf16 v[112:127], v[178:181], v[170:173], v[112:127]
	v_mfma_f32_32x32x16_bf16 v[96:111], v[178:181], v[174:177], v[96:111]
	v_mfma_f32_32x32x16_bf16 v[80:95], v[182:185], v[170:173], v[80:95]
	v_mfma_f32_32x32x16_bf16 v[64:79], v[182:185], v[174:177], v[64:79]
	s_setprio 0
	ds_read_b128 v[206:209], v233 offset:49152
	ds_read_b128 v[210:213], v233 offset:51200
	ds_read_b128 v[214:217], v231 offset:49152
	ds_read_b128 v[218:221], v231 offset:51200
	s_waitcnt lgkmcnt(4)
	s_setprio 1
	v_mfma_f32_32x32x16_bf16 v[48:63], v[186:189], v[170:173], v[48:63]
	v_mfma_f32_32x32x16_bf16 v[32:47], v[186:189], v[174:177], v[32:47]
	v_mfma_f32_32x32x16_bf16 v[16:31], v[190:193], v[170:173], v[16:31]
	v_mfma_f32_32x32x16_bf16 v[0:15], v[190:193], v[174:177], v[0:15]
	s_setprio 0
	ds_read_b128 v[222:225], v231 offset:53248
	ds_read_b128 v[226:229], v231 offset:55296
	s_waitcnt lgkmcnt(2)
	s_setprio 1
	v_mfma_f32_32x32x16_bf16 v[112:127], v[214:217], v[206:209], v[112:127]
	v_mfma_f32_32x32x16_bf16 v[96:111], v[214:217], v[210:213], v[96:111]
	v_mfma_f32_32x32x16_bf16 v[80:95], v[218:221], v[206:209], v[80:95]
	v_mfma_f32_32x32x16_bf16 v[64:79], v[218:221], v[210:213], v[64:79]
	s_setprio 0
	s_waitcnt vmcnt(0) lgkmcnt(0)
	s_barrier
	ds_read_b128 v[170:173], v232 offset:0
	ds_read_b128 v[174:177], v232 offset:2048
	ds_read_b128 v[178:181], v230 offset:0
	ds_read_b128 v[182:185], v230 offset:2048
	ds_read_b128 v[186:189], v230 offset:4096
	ds_read_b128 v[190:193], v230 offset:6144
	s_setprio 1
	v_mfma_f32_32x32x16_bf16 v[48:63], v[222:225], v[206:209], v[48:63]
	v_mfma_f32_32x32x16_bf16 v[32:47], v[222:225], v[210:213], v[32:47]
	v_mfma_f32_32x32x16_bf16 v[16:31], v[226:229], v[206:209], v[16:31]
	v_mfma_f32_32x32x16_bf16 v[0:15], v[226:229], v[210:213], v[0:15]
	s_setprio 0
	s_waitcnt lgkmcnt(2)
	s_setprio 1
	v_mfma_f32_32x32x16_bf16 v[112:127], v[178:181], v[170:173], v[112:127]
	v_mfma_f32_32x32x16_bf16 v[96:111], v[178:181], v[174:177], v[96:111]
	v_mfma_f32_32x32x16_bf16 v[80:95], v[182:185], v[170:173], v[80:95]
	v_mfma_f32_32x32x16_bf16 v[64:79], v[182:185], v[174:177], v[64:79]
	s_setprio 0
	ds_read_b128 v[206:209], v233 offset:0
	ds_read_b128 v[210:213], v233 offset:2048
	ds_read_b128 v[214:217], v231 offset:0
	ds_read_b128 v[218:221], v231 offset:2048
	s_waitcnt lgkmcnt(4)
	s_setprio 1
	v_mfma_f32_32x32x16_bf16 v[48:63], v[186:189], v[170:173], v[48:63]
	v_mfma_f32_32x32x16_bf16 v[32:47], v[186:189], v[174:177], v[32:47]
	v_mfma_f32_32x32x16_bf16 v[16:31], v[190:193], v[170:173], v[16:31]
	v_mfma_f32_32x32x16_bf16 v[0:15], v[190:193], v[174:177], v[0:15]
	s_setprio 0
	ds_read_b128 v[222:225], v231 offset:4096
	ds_read_b128 v[226:229], v231 offset:6144
	s_waitcnt lgkmcnt(2)
	s_setprio 1
	v_mfma_f32_32x32x16_bf16 v[112:127], v[214:217], v[206:209], v[112:127]
	v_mfma_f32_32x32x16_bf16 v[96:111], v[214:217], v[210:213], v[96:111]
	v_mfma_f32_32x32x16_bf16 v[80:95], v[218:221], v[206:209], v[80:95]
	v_mfma_f32_32x32x16_bf16 v[64:79], v[218:221], v[210:213], v[64:79]
	s_setprio 0
	s_waitcnt lgkmcnt(0)
	s_setprio 1
	v_mfma_f32_32x32x16_bf16 v[48:63], v[222:225], v[206:209], v[48:63]
	v_mfma_f32_32x32x16_bf16 v[32:47], v[222:225], v[210:213], v[32:47]
	v_mfma_f32_32x32x16_bf16 v[16:31], v[226:229], v[206:209], v[16:31]
	v_mfma_f32_32x32x16_bf16 v[0:15], v[226:229], v[210:213], v[0:15]
	s_setprio 0
	s_mul_hi_i32 s41, s42, 0x540000
	s_mul_i32 s42, s42, 0x540000
	s_add_u32 s42, s31, s42
	s_addc_u32 s43, s33, s41
	s_lshl_b32 s40, s40, 7
	s_ashr_i32 s41, s40, 31
	v_mov_b32_e32 v128, v204
	s_waitcnt vmcnt(0)
	s_barrier
	s_lshl_b64 s[40:41], s[40:41], 1
	s_add_u32 s40, s42, s40
	v_and_b32_e32 v132, 1, v128
	v_lshrrev_b32_e32 v130, 3, v128
	v_and_b32_e32 v131, 0x7fff81, v128
	v_and_b32_e32 v128, 0x5e, v128
	s_addc_u32 s41, s43, s41
	v_lshlrev_b32_e32 v128, 1, v128
	v_cmp_eq_u32_e32 vcc, 0, v132
	v_and_or_b32 v133, v130, 4, v131
	v_lshl_add_u64 v[130:131], s[40:41], 0, v[128:129]
	v_cndmask_b32_e32 v128, v112, v113, vcc
	s_add_i32 s16, s16, s17
	s_add_i32 s47, s47, s17
	v_mov_b32_dpp v128, v128 quad_perm:[1,0,3,2] row_mask:0xf bank_mask:0xf bound_ctrl:1
	v_cndmask_b32_e32 v113, v113, v128, vcc
	v_cndmask_b32_e32 v112, v128, v112, vcc
	v_cvt_pk_bf16_f32 v128, v112, v113
	v_mul_u32_u24_e32 v112, 0x2a00, v133
	v_ashrrev_i32_e32 v113, 31, v112
	v_lshl_add_u64 v[112:113], v[112:113], 1, v[130:131]
	global_store_dword v[112:113], v128, off
	v_cndmask_b32_e32 v128, v114, v115, vcc
	s_cmp_ge_i32 s16, s22
	s_cselect_b64 s[40:41], -1, 0
	v_mov_b32_dpp v128, v128 quad_perm:[1,0,3,2] row_mask:0xf bank_mask:0xf bound_ctrl:1
	v_cndmask_b32_e32 v115, v115, v128, vcc
	v_cndmask_b32_e32 v114, v128, v114, vcc
	v_cvt_pk_bf16_f32 v128, v114, v115
	v_mad_u32_u24 v114, v133, s48, v134
	v_ashrrev_i32_e32 v115, 31, v114
	v_lshl_add_u64 v[114:115], v[114:115], 1, v[130:131]
	global_store_dword v[114:115], v128, off
	v_cndmask_b32_e32 v128, v116, v117, vcc
	s_nop 1
	v_mov_b32_dpp v128, v128 quad_perm:[1,0,3,2] row_mask:0xf bank_mask:0xf bound_ctrl:1
	v_cndmask_b32_e32 v117, v117, v128, vcc
	v_cndmask_b32_e32 v116, v128, v116, vcc
	v_cvt_pk_bf16_f32 v128, v116, v117
	v_mad_u32_u24 v116, v133, s48, v135
	v_ashrrev_i32_e32 v117, 31, v116
	v_lshl_add_u64 v[116:117], v[116:117], 1, v[130:131]
	global_store_dword v[116:117], v128, off
	v_cndmask_b32_e32 v128, v118, v119, vcc
	s_nop 1
	v_mov_b32_dpp v128, v128 quad_perm:[1,0,3,2] row_mask:0xf bank_mask:0xf bound_ctrl:1
	v_cndmask_b32_e32 v119, v119, v128, vcc
	v_cndmask_b32_e32 v118, v128, v118, vcc
	v_cvt_pk_bf16_f32 v128, v118, v119
	v_mad_u32_u24 v118, v133, s48, v136
	v_ashrrev_i32_e32 v119, 31, v118
	v_lshl_add_u64 v[118:119], v[118:119], 1, v[130:131]
	global_store_dword v[118:119], v128, off
	v_cndmask_b32_e32 v128, v120, v121, vcc
	s_nop 1
	v_mov_b32_dpp v128, v128 quad_perm:[1,0,3,2] row_mask:0xf bank_mask:0xf bound_ctrl:1
	v_cndmask_b32_e32 v121, v121, v128, vcc
	v_cndmask_b32_e32 v120, v128, v120, vcc
	v_cvt_pk_bf16_f32 v128, v120, v121
	v_mad_u32_u24 v120, v133, s48, v137
	v_ashrrev_i32_e32 v121, 31, v120
	v_lshl_add_u64 v[120:121], v[120:121], 1, v[130:131]
	global_store_dword v[120:121], v128, off
	v_cndmask_b32_e32 v128, v122, v123, vcc
	s_nop 1
	v_mov_b32_dpp v128, v128 quad_perm:[1,0,3,2] row_mask:0xf bank_mask:0xf bound_ctrl:1
	v_cndmask_b32_e32 v123, v123, v128, vcc
	v_cndmask_b32_e32 v122, v128, v122, vcc
	v_cvt_pk_bf16_f32 v128, v122, v123
	v_mad_u32_u24 v122, v133, s48, v138
	v_ashrrev_i32_e32 v123, 31, v122
	v_lshl_add_u64 v[122:123], v[122:123], 1, v[130:131]
	global_store_dword v[122:123], v128, off
	v_cndmask_b32_e32 v128, v124, v125, vcc
	s_nop 1
	v_mov_b32_dpp v128, v128 quad_perm:[1,0,3,2] row_mask:0xf bank_mask:0xf bound_ctrl:1
	v_cndmask_b32_e32 v125, v125, v128, vcc
	v_cndmask_b32_e32 v124, v128, v124, vcc
	v_cvt_pk_bf16_f32 v128, v124, v125
	v_mad_u32_u24 v124, v133, s48, v139
	v_ashrrev_i32_e32 v125, 31, v124
	v_lshl_add_u64 v[124:125], v[124:125], 1, v[130:131]
	global_store_dword v[124:125], v128, off
	v_cndmask_b32_e32 v128, v126, v127, vcc
	s_nop 1
	v_mov_b32_dpp v128, v128 quad_perm:[1,0,3,2] row_mask:0xf bank_mask:0xf bound_ctrl:1
	v_cndmask_b32_e32 v127, v127, v128, vcc
	v_cndmask_b32_e32 v126, v128, v126, vcc
	v_cvt_pk_bf16_f32 v128, v126, v127
	v_mad_u32_u24 v126, v133, s48, v140
	v_ashrrev_i32_e32 v127, 31, v126
	v_lshl_add_u64 v[126:127], v[126:127], 1, v[130:131]
	global_store_dword v[126:127], v128, off
	v_cndmask_b32_e32 v128, v96, v97, vcc
	s_nop 1
	v_mov_b32_dpp v128, v128 quad_perm:[1,0,3,2] row_mask:0xf bank_mask:0xf bound_ctrl:1
	v_cndmask_b32_e32 v97, v97, v128, vcc
	v_cndmask_b32_e32 v96, v128, v96, vcc
	v_cvt_pk_bf16_f32 v96, v96, v97
	global_store_dword v[112:113], v96, off offset:64
	v_cndmask_b32_e32 v96, v98, v99, vcc
	s_nop 1
	v_mov_b32_dpp v96, v96 quad_perm:[1,0,3,2] row_mask:0xf bank_mask:0xf bound_ctrl:1
	v_cndmask_b32_e32 v97, v99, v96, vcc
	v_cndmask_b32_e32 v96, v96, v98, vcc
	v_cvt_pk_bf16_f32 v96, v96, v97
	global_store_dword v[114:115], v96, off offset:64
	v_cndmask_b32_e32 v96, v100, v101, vcc
	s_nop 1
	v_mov_b32_dpp v96, v96 quad_perm:[1,0,3,2] row_mask:0xf bank_mask:0xf bound_ctrl:1
	v_cndmask_b32_e32 v97, v101, v96, vcc
	v_cndmask_b32_e32 v96, v96, v100, vcc
	v_cvt_pk_bf16_f32 v96, v96, v97
	global_store_dword v[116:117], v96, off offset:64
	v_cndmask_b32_e32 v96, v102, v103, vcc
	s_nop 1
	v_mov_b32_dpp v96, v96 quad_perm:[1,0,3,2] row_mask:0xf bank_mask:0xf bound_ctrl:1
	v_cndmask_b32_e32 v97, v103, v96, vcc
	v_cndmask_b32_e32 v96, v96, v102, vcc
	v_cvt_pk_bf16_f32 v96, v96, v97
	global_store_dword v[118:119], v96, off offset:64
	v_cndmask_b32_e32 v96, v104, v105, vcc
	s_nop 1
	v_mov_b32_dpp v96, v96 quad_perm:[1,0,3,2] row_mask:0xf bank_mask:0xf bound_ctrl:1
	v_cndmask_b32_e32 v97, v105, v96, vcc
	v_cndmask_b32_e32 v96, v96, v104, vcc
	v_cvt_pk_bf16_f32 v96, v96, v97
	global_store_dword v[120:121], v96, off offset:64
	v_cndmask_b32_e32 v96, v106, v107, vcc
	s_nop 1
	v_mov_b32_dpp v96, v96 quad_perm:[1,0,3,2] row_mask:0xf bank_mask:0xf bound_ctrl:1
	v_cndmask_b32_e32 v97, v107, v96, vcc
	v_cndmask_b32_e32 v96, v96, v106, vcc
	v_cvt_pk_bf16_f32 v96, v96, v97
	global_store_dword v[122:123], v96, off offset:64
	v_cndmask_b32_e32 v96, v108, v109, vcc
	s_nop 1
	v_mov_b32_dpp v96, v96 quad_perm:[1,0,3,2] row_mask:0xf bank_mask:0xf bound_ctrl:1
	v_cndmask_b32_e32 v97, v109, v96, vcc
	v_cndmask_b32_e32 v96, v96, v108, vcc
	v_cvt_pk_bf16_f32 v96, v96, v97
	global_store_dword v[124:125], v96, off offset:64
	v_cndmask_b32_e32 v96, v110, v111, vcc
	s_nop 1
	v_mov_b32_dpp v96, v96 quad_perm:[1,0,3,2] row_mask:0xf bank_mask:0xf bound_ctrl:1
	v_cndmask_b32_e32 v97, v111, v96, vcc
	v_cndmask_b32_e32 v96, v96, v110, vcc
	v_cvt_pk_bf16_f32 v96, v96, v97
	global_store_dword v[126:127], v96, off offset:64
	v_cndmask_b32_e32 v96, v80, v81, vcc
	s_nop 1
	v_mov_b32_dpp v96, v96 quad_perm:[1,0,3,2] row_mask:0xf bank_mask:0xf bound_ctrl:1
	v_cndmask_b32_e32 v81, v81, v96, vcc
	v_cndmask_b32_e32 v80, v96, v80, vcc
	v_cvt_pk_bf16_f32 v96, v80, v81
	v_mad_u32_u24 v80, v133, s48, v141
	v_ashrrev_i32_e32 v81, 31, v80
	v_lshl_add_u64 v[80:81], v[80:81], 1, v[130:131]
	global_store_dword v[80:81], v96, off
	v_cndmask_b32_e32 v96, v82, v83, vcc
	s_nop 1
	v_mov_b32_dpp v96, v96 quad_perm:[1,0,3,2] row_mask:0xf bank_mask:0xf bound_ctrl:1
	v_cndmask_b32_e32 v83, v83, v96, vcc
	v_cndmask_b32_e32 v82, v96, v82, vcc
	v_cvt_pk_bf16_f32 v96, v82, v83
	v_mad_u32_u24 v82, v133, s48, v142
	v_ashrrev_i32_e32 v83, 31, v82
	v_lshl_add_u64 v[82:83], v[82:83], 1, v[130:131]
	global_store_dword v[82:83], v96, off
	v_cndmask_b32_e32 v96, v84, v85, vcc
	s_nop 1
	v_mov_b32_dpp v96, v96 quad_perm:[1,0,3,2] row_mask:0xf bank_mask:0xf bound_ctrl:1
	v_cndmask_b32_e32 v85, v85, v96, vcc
	v_cndmask_b32_e32 v84, v96, v84, vcc
	v_cvt_pk_bf16_f32 v96, v84, v85
	v_mad_u32_u24 v84, v133, s48, v143
	v_ashrrev_i32_e32 v85, 31, v84
	v_lshl_add_u64 v[84:85], v[84:85], 1, v[130:131]
	global_store_dword v[84:85], v96, off
	v_cndmask_b32_e32 v96, v86, v87, vcc
	s_nop 1
	v_mov_b32_dpp v96, v96 quad_perm:[1,0,3,2] row_mask:0xf bank_mask:0xf bound_ctrl:1
	v_cndmask_b32_e32 v87, v87, v96, vcc
	v_cndmask_b32_e32 v86, v96, v86, vcc
	v_cvt_pk_bf16_f32 v96, v86, v87
	v_mad_u32_u24 v86, v133, s48, v144
	v_ashrrev_i32_e32 v87, 31, v86
	v_lshl_add_u64 v[86:87], v[86:87], 1, v[130:131]
	global_store_dword v[86:87], v96, off
	v_cndmask_b32_e32 v96, v88, v89, vcc
	s_nop 1
	v_mov_b32_dpp v96, v96 quad_perm:[1,0,3,2] row_mask:0xf bank_mask:0xf bound_ctrl:1
	v_cndmask_b32_e32 v89, v89, v96, vcc
	v_cndmask_b32_e32 v88, v96, v88, vcc
	v_cvt_pk_bf16_f32 v96, v88, v89
	v_mad_u32_u24 v88, v133, s48, v145
	v_ashrrev_i32_e32 v89, 31, v88
	v_lshl_add_u64 v[88:89], v[88:89], 1, v[130:131]
	global_store_dword v[88:89], v96, off
	v_cndmask_b32_e32 v96, v90, v91, vcc
	s_nop 1
	v_mov_b32_dpp v96, v96 quad_perm:[1,0,3,2] row_mask:0xf bank_mask:0xf bound_ctrl:1
	v_cndmask_b32_e32 v91, v91, v96, vcc
	v_cndmask_b32_e32 v90, v96, v90, vcc
	v_cvt_pk_bf16_f32 v96, v90, v91
	v_mad_u32_u24 v90, v133, s48, v146
	v_ashrrev_i32_e32 v91, 31, v90
	v_lshl_add_u64 v[90:91], v[90:91], 1, v[130:131]
	global_store_dword v[90:91], v96, off
	v_cndmask_b32_e32 v96, v92, v93, vcc
	s_nop 1
	v_mov_b32_dpp v96, v96 quad_perm:[1,0,3,2] row_mask:0xf bank_mask:0xf bound_ctrl:1
	v_cndmask_b32_e32 v93, v93, v96, vcc
	v_cndmask_b32_e32 v92, v96, v92, vcc
	v_cvt_pk_bf16_f32 v96, v92, v93
	v_mad_u32_u24 v92, v133, s48, v147
	v_ashrrev_i32_e32 v93, 31, v92
	v_lshl_add_u64 v[92:93], v[92:93], 1, v[130:131]
	global_store_dword v[92:93], v96, off
	v_cndmask_b32_e32 v96, v94, v95, vcc
	s_nop 1
	v_mov_b32_dpp v96, v96 quad_perm:[1,0,3,2] row_mask:0xf bank_mask:0xf bound_ctrl:1
	v_cndmask_b32_e32 v95, v95, v96, vcc
	v_cndmask_b32_e32 v94, v96, v94, vcc
	v_cvt_pk_bf16_f32 v96, v94, v95
	v_mad_u32_u24 v94, v133, s48, v148
	v_ashrrev_i32_e32 v95, 31, v94
	v_lshl_add_u64 v[94:95], v[94:95], 1, v[130:131]
	global_store_dword v[94:95], v96, off
	v_cndmask_b32_e32 v96, v64, v65, vcc
	s_nop 1
	v_mov_b32_dpp v96, v96 quad_perm:[1,0,3,2] row_mask:0xf bank_mask:0xf bound_ctrl:1
	v_cndmask_b32_e32 v65, v65, v96, vcc
	v_cndmask_b32_e32 v64, v96, v64, vcc
	v_cvt_pk_bf16_f32 v64, v64, v65
	global_store_dword v[80:81], v64, off offset:64
	v_cndmask_b32_e32 v64, v66, v67, vcc
	s_nop 1
	v_mov_b32_dpp v64, v64 quad_perm:[1,0,3,2] row_mask:0xf bank_mask:0xf bound_ctrl:1
	v_cndmask_b32_e32 v65, v67, v64, vcc
	v_cndmask_b32_e32 v64, v64, v66, vcc
	v_cvt_pk_bf16_f32 v64, v64, v65
	global_store_dword v[82:83], v64, off offset:64
	v_cndmask_b32_e32 v64, v68, v69, vcc
	s_nop 1
	v_mov_b32_dpp v64, v64 quad_perm:[1,0,3,2] row_mask:0xf bank_mask:0xf bound_ctrl:1
	v_cndmask_b32_e32 v65, v69, v64, vcc
	v_cndmask_b32_e32 v64, v64, v68, vcc
	v_cvt_pk_bf16_f32 v64, v64, v65
	global_store_dword v[84:85], v64, off offset:64
	v_cndmask_b32_e32 v64, v70, v71, vcc
	s_nop 1
	v_mov_b32_dpp v64, v64 quad_perm:[1,0,3,2] row_mask:0xf bank_mask:0xf bound_ctrl:1
	v_cndmask_b32_e32 v65, v71, v64, vcc
	v_cndmask_b32_e32 v64, v64, v70, vcc
	v_cvt_pk_bf16_f32 v64, v64, v65
	global_store_dword v[86:87], v64, off offset:64
	v_cndmask_b32_e32 v64, v72, v73, vcc
	s_nop 1
	v_mov_b32_dpp v64, v64 quad_perm:[1,0,3,2] row_mask:0xf bank_mask:0xf bound_ctrl:1
	v_cndmask_b32_e32 v65, v73, v64, vcc
	v_cndmask_b32_e32 v64, v64, v72, vcc
	v_cvt_pk_bf16_f32 v64, v64, v65
	global_store_dword v[88:89], v64, off offset:64
	v_cndmask_b32_e32 v64, v74, v75, vcc
	s_nop 1
	v_mov_b32_dpp v64, v64 quad_perm:[1,0,3,2] row_mask:0xf bank_mask:0xf bound_ctrl:1
	v_cndmask_b32_e32 v65, v75, v64, vcc
	v_cndmask_b32_e32 v64, v64, v74, vcc
	v_cvt_pk_bf16_f32 v64, v64, v65
	global_store_dword v[90:91], v64, off offset:64
	v_cndmask_b32_e32 v64, v76, v77, vcc
	s_nop 1
	v_mov_b32_dpp v64, v64 quad_perm:[1,0,3,2] row_mask:0xf bank_mask:0xf bound_ctrl:1
	v_cndmask_b32_e32 v65, v77, v64, vcc
	v_cndmask_b32_e32 v64, v64, v76, vcc
	v_cvt_pk_bf16_f32 v64, v64, v65
	global_store_dword v[92:93], v64, off offset:64
	v_cndmask_b32_e32 v64, v78, v79, vcc
	s_nop 1
	v_mov_b32_dpp v64, v64 quad_perm:[1,0,3,2] row_mask:0xf bank_mask:0xf bound_ctrl:1
	v_cndmask_b32_e32 v65, v79, v64, vcc
	v_cndmask_b32_e32 v64, v64, v78, vcc
	v_cvt_pk_bf16_f32 v64, v64, v65
	global_store_dword v[94:95], v64, off offset:64
	v_cndmask_b32_e32 v64, v48, v49, vcc
	s_nop 1
	v_mov_b32_dpp v64, v64 quad_perm:[1,0,3,2] row_mask:0xf bank_mask:0xf bound_ctrl:1
	v_cndmask_b32_e32 v49, v49, v64, vcc
	v_cndmask_b32_e32 v48, v64, v48, vcc
	v_cvt_pk_bf16_f32 v64, v48, v49
	v_mad_u32_u24 v48, v133, s48, v149
	v_ashrrev_i32_e32 v49, 31, v48
	v_lshl_add_u64 v[48:49], v[48:49], 1, v[130:131]
	global_store_dword v[48:49], v64, off
	v_cndmask_b32_e32 v64, v50, v51, vcc
	s_nop 1
	v_mov_b32_dpp v64, v64 quad_perm:[1,0,3,2] row_mask:0xf bank_mask:0xf bound_ctrl:1
	v_cndmask_b32_e32 v51, v51, v64, vcc
	v_cndmask_b32_e32 v50, v64, v50, vcc
	v_cvt_pk_bf16_f32 v64, v50, v51
	v_mad_u32_u24 v50, v133, s48, v150
	v_ashrrev_i32_e32 v51, 31, v50
	v_lshl_add_u64 v[50:51], v[50:51], 1, v[130:131]
	global_store_dword v[50:51], v64, off
	v_cndmask_b32_e32 v64, v52, v53, vcc
	s_nop 1
	v_mov_b32_dpp v64, v64 quad_perm:[1,0,3,2] row_mask:0xf bank_mask:0xf bound_ctrl:1
	v_cndmask_b32_e32 v53, v53, v64, vcc
	v_cndmask_b32_e32 v52, v64, v52, vcc
	v_cvt_pk_bf16_f32 v64, v52, v53
	v_mad_u32_u24 v52, v133, s48, v151
	v_ashrrev_i32_e32 v53, 31, v52
	v_lshl_add_u64 v[52:53], v[52:53], 1, v[130:131]
	global_store_dword v[52:53], v64, off
	v_cndmask_b32_e32 v64, v54, v55, vcc
	s_nop 1
	v_mov_b32_dpp v64, v64 quad_perm:[1,0,3,2] row_mask:0xf bank_mask:0xf bound_ctrl:1
	v_cndmask_b32_e32 v55, v55, v64, vcc
	v_cndmask_b32_e32 v54, v64, v54, vcc
	v_cvt_pk_bf16_f32 v64, v54, v55
	v_mad_u32_u24 v54, v133, s48, v152
	v_ashrrev_i32_e32 v55, 31, v54
	v_lshl_add_u64 v[54:55], v[54:55], 1, v[130:131]
	global_store_dword v[54:55], v64, off
	v_cndmask_b32_e32 v64, v56, v57, vcc
	s_nop 1
	v_mov_b32_dpp v64, v64 quad_perm:[1,0,3,2] row_mask:0xf bank_mask:0xf bound_ctrl:1
	v_cndmask_b32_e32 v57, v57, v64, vcc
	v_cndmask_b32_e32 v56, v64, v56, vcc
	v_cvt_pk_bf16_f32 v64, v56, v57
	v_mad_u32_u24 v56, v133, s48, v153
	v_ashrrev_i32_e32 v57, 31, v56
	v_lshl_add_u64 v[56:57], v[56:57], 1, v[130:131]
	global_store_dword v[56:57], v64, off
	v_cndmask_b32_e32 v64, v58, v59, vcc
	s_nop 1
	v_mov_b32_dpp v64, v64 quad_perm:[1,0,3,2] row_mask:0xf bank_mask:0xf bound_ctrl:1
	v_cndmask_b32_e32 v59, v59, v64, vcc
	v_cndmask_b32_e32 v58, v64, v58, vcc
	v_cvt_pk_bf16_f32 v64, v58, v59
	v_mad_u32_u24 v58, v133, s48, v154
	v_ashrrev_i32_e32 v59, 31, v58
	v_lshl_add_u64 v[58:59], v[58:59], 1, v[130:131]
	global_store_dword v[58:59], v64, off
	v_cndmask_b32_e32 v64, v60, v61, vcc
	s_nop 1
	v_mov_b32_dpp v64, v64 quad_perm:[1,0,3,2] row_mask:0xf bank_mask:0xf bound_ctrl:1
	v_cndmask_b32_e32 v61, v61, v64, vcc
	v_cndmask_b32_e32 v60, v64, v60, vcc
	v_cvt_pk_bf16_f32 v64, v60, v61
	v_mad_u32_u24 v60, v133, s48, v155
	v_ashrrev_i32_e32 v61, 31, v60
	v_lshl_add_u64 v[60:61], v[60:61], 1, v[130:131]
	global_store_dword v[60:61], v64, off
	v_cndmask_b32_e32 v64, v62, v63, vcc
	s_nop 1
	v_mov_b32_dpp v64, v64 quad_perm:[1,0,3,2] row_mask:0xf bank_mask:0xf bound_ctrl:1
	v_cndmask_b32_e32 v63, v63, v64, vcc
	v_cndmask_b32_e32 v62, v64, v62, vcc
	v_cvt_pk_bf16_f32 v64, v62, v63
	v_mad_u32_u24 v62, v133, s48, v156
	v_ashrrev_i32_e32 v63, 31, v62
	v_lshl_add_u64 v[62:63], v[62:63], 1, v[130:131]
	global_store_dword v[62:63], v64, off
	v_cndmask_b32_e32 v64, v32, v33, vcc
	s_nop 1
	v_mov_b32_dpp v64, v64 quad_perm:[1,0,3,2] row_mask:0xf bank_mask:0xf bound_ctrl:1
	v_cndmask_b32_e32 v33, v33, v64, vcc
	v_cndmask_b32_e32 v32, v64, v32, vcc
	v_cvt_pk_bf16_f32 v32, v32, v33
	global_store_dword v[48:49], v32, off offset:64
	v_cndmask_b32_e32 v32, v34, v35, vcc
	s_nop 1
	v_mov_b32_dpp v32, v32 quad_perm:[1,0,3,2] row_mask:0xf bank_mask:0xf bound_ctrl:1
	v_cndmask_b32_e32 v33, v35, v32, vcc
	v_cndmask_b32_e32 v32, v32, v34, vcc
	v_cvt_pk_bf16_f32 v32, v32, v33
	global_store_dword v[50:51], v32, off offset:64
	v_cndmask_b32_e32 v32, v36, v37, vcc
	s_nop 1
	v_mov_b32_dpp v32, v32 quad_perm:[1,0,3,2] row_mask:0xf bank_mask:0xf bound_ctrl:1
	v_cndmask_b32_e32 v33, v37, v32, vcc
	v_cndmask_b32_e32 v32, v32, v36, vcc
	v_cvt_pk_bf16_f32 v32, v32, v33
	global_store_dword v[52:53], v32, off offset:64
	v_cndmask_b32_e32 v32, v38, v39, vcc
	s_nop 1
	v_mov_b32_dpp v32, v32 quad_perm:[1,0,3,2] row_mask:0xf bank_mask:0xf bound_ctrl:1
	v_cndmask_b32_e32 v33, v39, v32, vcc
	v_cndmask_b32_e32 v32, v32, v38, vcc
	v_cvt_pk_bf16_f32 v32, v32, v33
	global_store_dword v[54:55], v32, off offset:64
	v_cndmask_b32_e32 v32, v40, v41, vcc
	s_nop 1
	v_mov_b32_dpp v32, v32 quad_perm:[1,0,3,2] row_mask:0xf bank_mask:0xf bound_ctrl:1
	v_cndmask_b32_e32 v33, v41, v32, vcc
	v_cndmask_b32_e32 v32, v32, v40, vcc
	v_cvt_pk_bf16_f32 v32, v32, v33
	global_store_dword v[56:57], v32, off offset:64
	v_cndmask_b32_e32 v32, v42, v43, vcc
	s_nop 1
	v_mov_b32_dpp v32, v32 quad_perm:[1,0,3,2] row_mask:0xf bank_mask:0xf bound_ctrl:1
	v_cndmask_b32_e32 v33, v43, v32, vcc
	v_cndmask_b32_e32 v32, v32, v42, vcc
	v_cvt_pk_bf16_f32 v32, v32, v33
	global_store_dword v[58:59], v32, off offset:64
	v_cndmask_b32_e32 v32, v44, v45, vcc
	s_nop 1
	v_mov_b32_dpp v32, v32 quad_perm:[1,0,3,2] row_mask:0xf bank_mask:0xf bound_ctrl:1
	v_cndmask_b32_e32 v33, v45, v32, vcc
	v_cndmask_b32_e32 v32, v32, v44, vcc
	v_cvt_pk_bf16_f32 v32, v32, v33
	global_store_dword v[60:61], v32, off offset:64
	v_cndmask_b32_e32 v32, v46, v47, vcc
	s_nop 1
	v_mov_b32_dpp v32, v32 quad_perm:[1,0,3,2] row_mask:0xf bank_mask:0xf bound_ctrl:1
	v_cndmask_b32_e32 v33, v47, v32, vcc
	v_cndmask_b32_e32 v32, v32, v46, vcc
	v_cvt_pk_bf16_f32 v32, v32, v33
	global_store_dword v[62:63], v32, off offset:64
	v_cndmask_b32_e32 v32, v16, v17, vcc
	s_nop 1
	v_mov_b32_dpp v32, v32 quad_perm:[1,0,3,2] row_mask:0xf bank_mask:0xf bound_ctrl:1
	v_cndmask_b32_e32 v17, v17, v32, vcc
	v_cndmask_b32_e32 v16, v32, v16, vcc
	v_cvt_pk_bf16_f32 v32, v16, v17
	v_mad_u32_u24 v16, v133, s48, v157
	v_ashrrev_i32_e32 v17, 31, v16
	v_lshl_add_u64 v[16:17], v[16:17], 1, v[130:131]
	global_store_dword v[16:17], v32, off
	v_cndmask_b32_e32 v32, v18, v19, vcc
	s_nop 1
	v_mov_b32_dpp v32, v32 quad_perm:[1,0,3,2] row_mask:0xf bank_mask:0xf bound_ctrl:1
	v_cndmask_b32_e32 v19, v19, v32, vcc
	v_cndmask_b32_e32 v18, v32, v18, vcc
	v_cvt_pk_bf16_f32 v32, v18, v19
	v_mad_u32_u24 v18, v133, s48, v158
	v_ashrrev_i32_e32 v19, 31, v18
	v_lshl_add_u64 v[18:19], v[18:19], 1, v[130:131]
	global_store_dword v[18:19], v32, off
	v_cndmask_b32_e32 v32, v20, v21, vcc
	s_nop 1
	v_mov_b32_dpp v32, v32 quad_perm:[1,0,3,2] row_mask:0xf bank_mask:0xf bound_ctrl:1
	v_cndmask_b32_e32 v21, v21, v32, vcc
	v_cndmask_b32_e32 v20, v32, v20, vcc
	v_cvt_pk_bf16_f32 v32, v20, v21
	v_mad_u32_u24 v20, v133, s48, v159
	v_ashrrev_i32_e32 v21, 31, v20
	v_lshl_add_u64 v[20:21], v[20:21], 1, v[130:131]
	global_store_dword v[20:21], v32, off
	v_cndmask_b32_e32 v32, v22, v23, vcc
	s_nop 1
	v_mov_b32_dpp v32, v32 quad_perm:[1,0,3,2] row_mask:0xf bank_mask:0xf bound_ctrl:1
	v_cndmask_b32_e32 v23, v23, v32, vcc
	v_cndmask_b32_e32 v22, v32, v22, vcc
	v_cvt_pk_bf16_f32 v32, v22, v23
	v_mad_u32_u24 v22, v133, s48, v160
	v_ashrrev_i32_e32 v23, 31, v22
	v_lshl_add_u64 v[22:23], v[22:23], 1, v[130:131]
	global_store_dword v[22:23], v32, off
	v_cndmask_b32_e32 v32, v24, v25, vcc
	s_nop 1
	v_mov_b32_dpp v32, v32 quad_perm:[1,0,3,2] row_mask:0xf bank_mask:0xf bound_ctrl:1
	v_cndmask_b32_e32 v25, v25, v32, vcc
	v_cndmask_b32_e32 v24, v32, v24, vcc
	v_cvt_pk_bf16_f32 v32, v24, v25
	v_mad_u32_u24 v24, v133, s48, v161
	v_ashrrev_i32_e32 v25, 31, v24
	v_lshl_add_u64 v[24:25], v[24:25], 1, v[130:131]
	global_store_dword v[24:25], v32, off
	v_cndmask_b32_e32 v32, v26, v27, vcc
	s_nop 1
	v_mov_b32_dpp v32, v32 quad_perm:[1,0,3,2] row_mask:0xf bank_mask:0xf bound_ctrl:1
	v_cndmask_b32_e32 v27, v27, v32, vcc
	v_cndmask_b32_e32 v26, v32, v26, vcc
	v_cvt_pk_bf16_f32 v32, v26, v27
	v_mad_u32_u24 v26, v133, s48, v162
	v_ashrrev_i32_e32 v27, 31, v26
	v_lshl_add_u64 v[26:27], v[26:27], 1, v[130:131]
	global_store_dword v[26:27], v32, off
	v_cndmask_b32_e32 v32, v28, v29, vcc
	s_nop 1
	v_mov_b32_dpp v32, v32 quad_perm:[1,0,3,2] row_mask:0xf bank_mask:0xf bound_ctrl:1
	v_cndmask_b32_e32 v29, v29, v32, vcc
	v_cndmask_b32_e32 v28, v32, v28, vcc
	v_cvt_pk_bf16_f32 v32, v28, v29
	v_mad_u32_u24 v28, v133, s48, v163
	v_ashrrev_i32_e32 v29, 31, v28
	v_lshl_add_u64 v[28:29], v[28:29], 1, v[130:131]
	global_store_dword v[28:29], v32, off
	v_cndmask_b32_e32 v32, v30, v31, vcc
	s_nop 1
	v_mov_b32_dpp v32, v32 quad_perm:[1,0,3,2] row_mask:0xf bank_mask:0xf bound_ctrl:1
	v_cndmask_b32_e32 v31, v31, v32, vcc
	v_cndmask_b32_e32 v30, v32, v30, vcc
	v_cvt_pk_bf16_f32 v32, v30, v31
	v_mad_u32_u24 v30, v133, s48, v164
	v_ashrrev_i32_e32 v31, 31, v30
	v_lshl_add_u64 v[30:31], v[30:31], 1, v[130:131]
	global_store_dword v[30:31], v32, off
	v_cndmask_b32_e32 v32, v0, v1, vcc
	s_nop 1
	v_mov_b32_dpp v32, v32 quad_perm:[1,0,3,2] row_mask:0xf bank_mask:0xf bound_ctrl:1
	v_cndmask_b32_e32 v1, v1, v32, vcc
	v_cndmask_b32_e32 v0, v32, v0, vcc
	v_cvt_pk_bf16_f32 v0, v0, v1
	global_store_dword v[16:17], v0, off offset:64
	v_cndmask_b32_e32 v0, v2, v3, vcc
	s_nop 1
	v_mov_b32_dpp v0, v0 quad_perm:[1,0,3,2] row_mask:0xf bank_mask:0xf bound_ctrl:1
	v_cndmask_b32_e32 v1, v3, v0, vcc
	v_cndmask_b32_e32 v0, v0, v2, vcc
	v_cvt_pk_bf16_f32 v0, v0, v1
	global_store_dword v[18:19], v0, off offset:64
	v_cndmask_b32_e32 v0, v4, v5, vcc
	s_nop 1
	v_mov_b32_dpp v0, v0 quad_perm:[1,0,3,2] row_mask:0xf bank_mask:0xf bound_ctrl:1
	v_cndmask_b32_e32 v1, v5, v0, vcc
	v_cndmask_b32_e32 v0, v0, v4, vcc
	v_cvt_pk_bf16_f32 v0, v0, v1
	global_store_dword v[20:21], v0, off offset:64
	v_cndmask_b32_e32 v0, v6, v7, vcc
	s_nop 1
	v_mov_b32_dpp v0, v0 quad_perm:[1,0,3,2] row_mask:0xf bank_mask:0xf bound_ctrl:1
	v_cndmask_b32_e32 v1, v7, v0, vcc
	v_cndmask_b32_e32 v0, v0, v6, vcc
	v_cvt_pk_bf16_f32 v0, v0, v1
	global_store_dword v[22:23], v0, off offset:64
	v_cndmask_b32_e32 v0, v8, v9, vcc
	s_nop 1
	v_mov_b32_dpp v0, v0 quad_perm:[1,0,3,2] row_mask:0xf bank_mask:0xf bound_ctrl:1
	v_cndmask_b32_e32 v1, v9, v0, vcc
	v_cndmask_b32_e32 v0, v0, v8, vcc
	v_cvt_pk_bf16_f32 v0, v0, v1
	global_store_dword v[24:25], v0, off offset:64
	v_cndmask_b32_e32 v0, v10, v11, vcc
	s_nop 1
	v_mov_b32_dpp v0, v0 quad_perm:[1,0,3,2] row_mask:0xf bank_mask:0xf bound_ctrl:1
	v_cndmask_b32_e32 v1, v11, v0, vcc
	v_cndmask_b32_e32 v0, v0, v10, vcc
	v_cvt_pk_bf16_f32 v0, v0, v1
	global_store_dword v[26:27], v0, off offset:64
	v_cndmask_b32_e32 v0, v12, v13, vcc
	s_nop 1
	v_mov_b32_dpp v0, v0 quad_perm:[1,0,3,2] row_mask:0xf bank_mask:0xf bound_ctrl:1
	v_cndmask_b32_e32 v1, v13, v0, vcc
	v_cndmask_b32_e32 v0, v0, v12, vcc
	v_cvt_pk_bf16_f32 v0, v0, v1
	global_store_dword v[28:29], v0, off offset:64
	v_cndmask_b32_e32 v0, v14, v15, vcc
	s_nop 1
	v_mov_b32_dpp v0, v0 quad_perm:[1,0,3,2] row_mask:0xf bank_mask:0xf bound_ctrl:1
	v_cndmask_b32_e32 v1, v15, v0, vcc
	v_cndmask_b32_e32 v0, v0, v14, vcc
	v_cvt_pk_bf16_f32 v0, v0, v1
	global_store_dword v[30:31], v0, off offset:64
	s_branch .LBB0_126
